# v16 + GEMM K-loops: the s_setprio 0 / s_setprio 1 flip in the middle of each MFMA segment removed (one raise per segment)
# speedup vs baseline: 1.0142x; 1.0142x over previous
; #define PG8_STAGE(bufoff, gbase, voff) do { _Pragma("unroll") for (int _i = 0; _i < 2; ++_i) \
;         __builtin_amdgcn_global_load_lds((const unsigned*)((const char*)(gbase) + (voff)[_i]), (PG8_LAS unsigned*)(lds + (bufoff) + ldsw + _i * 8192), 16, 0, 0); } while (0)
; #define PG8_LDA(dst, b, h) do { _Pragma("unroll") for (int m = 0; m < 4; ++m) _Pragma("unroll") for (int k = 0; k < 2; ++k) dst[m][k] = *(const PG8_LAS bf16x8*)(lds + PG8_SA(b, h) + aoff + m * 2048 + k * 1024); } while (0)
; #define PG8_LDB(dst, b, h) do { _Pragma("unroll") for (int n = 0; n < 2; ++n) _Pragma("unroll") for (int k = 0; k < 2; ++k) dst[n][k] = *(const PG8_LAS bf16x8*)(lds + PG8_SB(b, h) + boff + n * 2048 + k * 1024); } while (0)
; #define PG8_MMA(ai, bj, At, Bt) do { __builtin_amdgcn_s_setprio(1); _Pragma("unroll") for (int m = 0; m < 4; ++m) _Pragma("unroll") for (int n = 0; n < 2; ++n) _Pragma("unroll") for (int k = 0; k < 2; ++k) \
;         acc[ai][bj][m][n] = __builtin_amdgcn_mfma_f32_16x16x32_bf16(Bt[n][k], At[m][k], acc[ai][bj][m][n], 0, 0, 0); __builtin_amdgcn_s_setprio(0); } while (0)
; #define PG8_WAIT_V(n) asm volatile("s_waitcnt vmcnt(" #n ")" ::: "memory")
; #define PG8_WAIT_L(n) asm volatile("s_waitcnt lgkmcnt(" #n ")" ::: "memory")
; template <class Epi, class Sched, bool ALIGN_EPI = false, bool SP2 = false>
; __device__ __forceinline__ void gemm_phase(PG8_LAS unsigned char* lds, const Gemm g, const Sched& S, const Epi& E, const int tid) {
;     ...
;             const bool last = (t == nt - 2);
;             const char* a1 = cA + (size_t)(t + 1) * kstep;
;             const char* a2 = last ? nA : cA + (size_t)(t + 2) * kstep; const char* b2 = last ? nB : cB + (size_t)(t + 2) * kstep;
;             const char* a3 = a2 + kstep; const char* b3 = b2 + kstep;
;             if (last && has_next) S.a_ready(nxt);
;             if constexpr (SP2) {
;             PG8_LDB(B0, 0, 0); PG8_LDB(B1, 0, 1); PG8_SCHED; PG8_LDA(At, 0, 0); PG8_STAGE(PG8_SA(1, 1), a1 + hstep, voffA);
;             PG8_WAIT_V(8); PG8_WAIT_L(0); PG8_BAR; PG8_MMA(0, 0, At, B0); PG8_MMA(0, 1, At, B1); PG8_BAR; PG8_SCHED;
;             PG8_LDA(At, 0, 1); PG8_STAGE(PG8_SB(0, 0), b2, voffB); PG8_STAGE(PG8_SB(0, 1), b2 + hstep, voffB); PG8_STAGE(PG8_SA(0, 0), a2, voffA);
;             PG8_WAIT_V(8); PG8_WAIT_L(0); PG8_BAR; PG8_MMA(1, 0, At, B0); PG8_MMA(1, 1, At, B1); PG8_BAR; PG8_SCHED;
.LBB0_126:
	s_add_u32 s26, s2, 0xfffc0080
	s_addc_u32 s27, s3, -1
	s_add_i32 s55, 0, 0x10000
	s_cmp_eq_u32 s54, 12
	s_cselect_b32 s29, s1, s27
	s_cselect_b32 s28, s21, s26
	v_add_u32_e32 v145, s55, v178
	s_cselect_b32 s27, s19, s53
	s_cselect_b32 s26, s51, s52
	s_add_i32 s58, 0, 0x14000
	ds_read_b128 v[128:131], v145
	ds_read_b128 v[132:135], v145 offset:1024
	ds_read_b128 v[164:167], v145 offset:2048
	ds_read_b128 v[168:171], v145 offset:3072
	v_add_u32_e32 v145, s58, v178
	ds_read_b128 v[172:175], v145
	ds_read_b128 v[180:183], v145 offset:1024
	ds_read_b128 v[184:187], v145 offset:2048
	ds_read_b128 v[188:191], v145 offset:3072
	v_lshl_add_u64 v[150:151], s[2:3], 0, v[160:161]
	s_add_i32 m0, s36, 0xc000
	ds_read_b128 v[192:195], v179
	ds_read_b128 v[196:199], v179 offset:1024
	ds_read_b128 v[200:203], v179 offset:2048
	ds_read_b128 v[222:225], v179 offset:3072
	ds_read_b128 v[226:229], v179 offset:4096
	ds_read_b128 v[230:233], v179 offset:5120
	ds_read_b128 v[234:237], v179 offset:6144
	ds_read_b128 v[238:241], v179 offset:7168
	global_load_lds_dwordx4 v[150:151], off
	v_lshl_add_u64 v[150:151], s[2:3], 0, v[162:163]
	s_add_i32 m0, s36, 0xe000
	s_nop 0
	global_load_lds_dwordx4 v[150:151], off
	s_waitcnt vmcnt(8)
	s_waitcnt lgkmcnt(0)
	s_barrier
	s_setprio 1
	s_waitcnt lgkmcnt(0)
	v_mfma_f32_16x16x32_bf16 v[124:127], v[128:131], v[192:195], v[124:127]
	v_mfma_f32_16x16x32_bf16 v[120:123], v[164:167], v[192:195], v[120:123]
	v_mfma_f32_16x16x32_bf16 v[108:111], v[128:131], v[200:203], v[108:111]
	v_mfma_f32_16x16x32_bf16 v[104:107], v[164:167], v[200:203], v[104:107]
	v_mfma_f32_16x16x32_bf16 v[92:95], v[128:131], v[226:229], v[92:95]
	v_mfma_f32_16x16x32_bf16 v[88:91], v[164:167], v[226:229], v[88:91]
	v_mfma_f32_16x16x32_bf16 v[76:79], v[128:131], v[234:237], v[76:79]
	v_mfma_f32_16x16x32_bf16 v[72:75], v[164:167], v[234:237], v[72:75]
	v_mfma_f32_16x16x32_bf16 v[124:127], v[132:135], v[196:199], v[124:127]
	v_mfma_f32_16x16x32_bf16 v[120:123], v[168:171], v[196:199], v[120:123]
	v_mfma_f32_16x16x32_bf16 v[108:111], v[132:135], v[222:225], v[108:111]
	v_mfma_f32_16x16x32_bf16 v[104:107], v[168:171], v[222:225], v[104:107]
	v_mfma_f32_16x16x32_bf16 v[92:95], v[132:135], v[230:233], v[92:95]
	v_mfma_f32_16x16x32_bf16 v[88:91], v[168:171], v[230:233], v[88:91]
	v_mfma_f32_16x16x32_bf16 v[76:79], v[132:135], v[238:241], v[76:79]
	v_mfma_f32_16x16x32_bf16 v[72:75], v[168:171], v[238:241], v[72:75]
	v_mfma_f32_16x16x32_bf16 v[116:119], v[172:175], v[192:195], v[116:119]
	v_mfma_f32_16x16x32_bf16 v[112:115], v[184:187], v[192:195], v[112:115]
	v_mfma_f32_16x16x32_bf16 v[100:103], v[172:175], v[200:203], v[100:103]
	v_mfma_f32_16x16x32_bf16 v[96:99], v[184:187], v[200:203], v[96:99]
	v_mfma_f32_16x16x32_bf16 v[84:87], v[172:175], v[226:229], v[84:87]
	v_mfma_f32_16x16x32_bf16 v[80:83], v[184:187], v[226:229], v[80:83]
	v_mfma_f32_16x16x32_bf16 v[68:71], v[172:175], v[234:237], v[68:71]
	v_mfma_f32_16x16x32_bf16 v[64:67], v[184:187], v[234:237], v[64:67]
	v_mfma_f32_16x16x32_bf16 v[116:119], v[180:183], v[196:199], v[116:119]
	v_mfma_f32_16x16x32_bf16 v[112:115], v[188:191], v[196:199], v[112:115]
	v_mfma_f32_16x16x32_bf16 v[100:103], v[180:183], v[222:225], v[100:103]
	v_mfma_f32_16x16x32_bf16 v[96:99], v[188:191], v[222:225], v[96:99]
	v_mfma_f32_16x16x32_bf16 v[84:87], v[180:183], v[230:233], v[84:87]
	v_mfma_f32_16x16x32_bf16 v[80:83], v[188:191], v[230:233], v[80:83]
	v_mfma_f32_16x16x32_bf16 v[68:71], v[180:183], v[238:241], v[68:71]
	v_mfma_f32_16x16x32_bf16 v[64:67], v[188:191], v[238:241], v[64:67]
	s_setprio 0
	s_barrier
	s_add_i32 s55, s55, s35
	v_lshl_add_u64 v[150:151], s[26:27], 0, v[138:139]
	s_mov_b32 m0, s55
	ds_read_b128 v[192:195], v179 offset:16384
	ds_read_b128 v[196:199], v179 offset:17408
	ds_read_b128 v[200:203], v179 offset:18432
	ds_read_b128 v[222:225], v179 offset:19456
	ds_read_b128 v[226:229], v179 offset:20480
	ds_read_b128 v[230:233], v179 offset:21504
	ds_read_b128 v[234:237], v179 offset:22528
	ds_read_b128 v[238:241], v179 offset:23552
	global_load_lds_dwordx4 v[150:151], off
	s_add_i32 m0, s55, 0x2000
	s_add_u32 s56, s26, 0x40000
	v_lshl_add_u64 v[176:177], s[26:27], 0, v[142:143]
	s_addc_u32 s57, s27, 0
	s_add_i32 s55, s58, s35
	global_load_lds_dwordx4 v[176:177], off
	v_lshl_add_u64 v[204:205], s[56:57], 0, v[138:139]
	s_mov_b32 m0, s55
	v_lshl_add_u64 v[206:207], s[28:29], 0, v[140:141]
	global_load_lds_dwordx4 v[204:205], off
	v_lshl_add_u64 v[204:205], s[56:57], 0, v[142:143]
	s_add_i32 m0, s55, 0x2000
	s_nop 0
	global_load_lds_dwordx4 v[204:205], off
	v_lshl_add_u64 v[204:205], s[28:29], 0, v[136:137]
	s_mov_b32 m0, s36
	s_nop 0
	global_load_lds_dwordx4 v[204:205], off
	s_mov_b32 m0, s37
	s_nop 0
	global_load_lds_dwordx4 v[206:207], off
	s_waitcnt vmcnt(8)
	s_waitcnt lgkmcnt(0)
	s_barrier
; #define PG8_STAGE(bufoff, gbase, voff) do { _Pragma("unroll") for (int _i = 0; _i < 2; ++_i) \
;         __builtin_amdgcn_global_load_lds((const unsigned*)((const char*)(gbase) + (voff)[_i]), (PG8_LAS unsigned*)(lds + (bufoff) + ldsw + _i * 8192), 16, 0, 0); } while (0)
; #define PG8_LDA(dst, b, h) do { _Pragma("unroll") for (int m = 0; m < 4; ++m) _Pragma("unroll") for (int k = 0; k < 2; ++k) dst[m][k] = *(const PG8_LAS bf16x8*)(lds + PG8_SA(b, h) + aoff + m * 2048 + k * 1024); } while (0)
; #define PG8_LDB(dst, b, h) do { _Pragma("unroll") for (int n = 0; n < 2; ++n) _Pragma("unroll") for (int k = 0; k < 2; ++k) dst[n][k] = *(const PG8_LAS bf16x8*)(lds + PG8_SB(b, h) + boff + n * 2048 + k * 1024); } while (0)
; #define PG8_MMA(ai, bj, At, Bt) do { __builtin_amdgcn_s_setprio(1); _Pragma("unroll") for (int m = 0; m < 4; ++m) _Pragma("unroll") for (int n = 0; n < 2; ++n) _Pragma("unroll") for (int k = 0; k < 2; ++k) \
;         acc[ai][bj][m][n] = __builtin_amdgcn_mfma_f32_16x16x32_bf16(Bt[n][k], At[m][k], acc[ai][bj][m][n], 0, 0, 0); __builtin_amdgcn_s_setprio(0); } while (0)
; #define PG8_WAIT_V(n) asm volatile("s_waitcnt vmcnt(" #n ")" ::: "memory")
; #define PG8_WAIT_L(n) asm volatile("s_waitcnt lgkmcnt(" #n ")" ::: "memory")
; #define PG8_BAR __builtin_amdgcn_s_barrier()
; #define PG8_SCHED __builtin_amdgcn_sched_barrier(0)
; template <class Epi, class Sched, bool ALIGN_EPI = false, bool SP2 = false>
; __device__ __forceinline__ void gemm_phase(PG8_LAS unsigned char* lds, const Gemm g, const Sched& S, const Epi& E, const int tid) {
;     ...
;             PG8_WAIT_V(8); PG8_WAIT_L(0); PG8_BAR; PG8_MMA(1, 0, At, B0); PG8_MMA(1, 1, At, B1); PG8_BAR; PG8_SCHED;
;             PG8_LDB(B0, 1, 0); PG8_LDB(B1, 1, 1); PG8_SCHED; PG8_LDA(At, 1, 0); PG8_STAGE(PG8_SA(0, 1), a2 + hstep, voffA);
;             PG8_WAIT_V(8); PG8_WAIT_L(0); PG8_BAR; PG8_MMA(0, 0, At, B0); PG8_MMA(0, 1, At, B1); PG8_BAR; PG8_SCHED;
	s_setprio 1
	s_waitcnt lgkmcnt(0)
	v_mfma_f32_16x16x32_bf16 v[60:63], v[128:131], v[192:195], v[60:63]
	v_mfma_f32_16x16x32_bf16 v[56:59], v[164:167], v[192:195], v[56:59]
	v_mfma_f32_16x16x32_bf16 v[44:47], v[128:131], v[200:203], v[44:47]
	v_mfma_f32_16x16x32_bf16 v[40:43], v[164:167], v[200:203], v[40:43]
	v_mfma_f32_16x16x32_bf16 v[28:31], v[128:131], v[226:229], v[28:31]
	v_mfma_f32_16x16x32_bf16 v[24:27], v[164:167], v[226:229], v[24:27]
	v_mfma_f32_16x16x32_bf16 v[12:15], v[128:131], v[234:237], v[12:15]
	v_mfma_f32_16x16x32_bf16 v[8:11], v[164:167], v[234:237], v[8:11]
	v_mfma_f32_16x16x32_bf16 v[60:63], v[132:135], v[196:199], v[60:63]
	v_mfma_f32_16x16x32_bf16 v[56:59], v[168:171], v[196:199], v[56:59]
	v_mfma_f32_16x16x32_bf16 v[44:47], v[132:135], v[222:225], v[44:47]
	v_mfma_f32_16x16x32_bf16 v[40:43], v[168:171], v[222:225], v[40:43]
	v_mfma_f32_16x16x32_bf16 v[28:31], v[132:135], v[230:233], v[28:31]
	v_mfma_f32_16x16x32_bf16 v[24:27], v[168:171], v[230:233], v[24:27]
	v_mfma_f32_16x16x32_bf16 v[12:15], v[132:135], v[238:241], v[12:15]
	v_mfma_f32_16x16x32_bf16 v[8:11], v[168:171], v[238:241], v[8:11]
	v_mfma_f32_16x16x32_bf16 v[52:55], v[172:175], v[192:195], v[52:55]
	v_mfma_f32_16x16x32_bf16 v[48:51], v[184:187], v[192:195], v[48:51]
	v_mfma_f32_16x16x32_bf16 v[36:39], v[172:175], v[200:203], v[36:39]
	v_mfma_f32_16x16x32_bf16 v[32:35], v[184:187], v[200:203], v[32:35]
	v_mfma_f32_16x16x32_bf16 v[20:23], v[172:175], v[226:229], v[20:23]
	v_mfma_f32_16x16x32_bf16 v[16:19], v[184:187], v[226:229], v[16:19]
	v_mfma_f32_16x16x32_bf16 v[4:7], v[172:175], v[234:237], v[4:7]
	v_mfma_f32_16x16x32_bf16 v[0:3], v[184:187], v[234:237], v[0:3]
	v_mfma_f32_16x16x32_bf16 v[52:55], v[180:183], v[196:199], v[52:55]
	v_mfma_f32_16x16x32_bf16 v[48:51], v[188:191], v[196:199], v[48:51]
	v_mfma_f32_16x16x32_bf16 v[36:39], v[180:183], v[222:225], v[36:39]
	v_mfma_f32_16x16x32_bf16 v[32:35], v[188:191], v[222:225], v[32:35]
	v_mfma_f32_16x16x32_bf16 v[20:23], v[180:183], v[230:233], v[20:23]
	v_mfma_f32_16x16x32_bf16 v[16:19], v[188:191], v[230:233], v[16:19]
	v_mfma_f32_16x16x32_bf16 v[4:7], v[180:183], v[238:241], v[4:7]
	v_mfma_f32_16x16x32_bf16 v[0:3], v[188:191], v[238:241], v[0:3]
	s_setprio 0
	s_barrier
	s_add_i32 s55, 0, 0x18000
	v_add_u32_e32 v145, s55, v178
	s_add_i32 s56, 0, 0x1c000
	ds_read_b128 v[128:131], v145
	ds_read_b128 v[132:135], v145 offset:1024
	ds_read_b128 v[164:167], v145 offset:2048
	ds_read_b128 v[168:171], v145 offset:3072
	v_add_u32_e32 v145, s56, v178
	ds_read_b128 v[172:175], v145
	ds_read_b128 v[180:183], v145 offset:1024
	ds_read_b128 v[184:187], v145 offset:2048
	ds_read_b128 v[188:191], v145 offset:3072
	s_add_u32 s28, s28, 0x40000
	s_addc_u32 s29, s29, 0
	s_mov_b32 m0, s38
	v_lshl_add_u64 v[242:243], s[28:29], 0, v[136:137]
	ds_read_b128 v[192:195], v179 offset:32768
	ds_read_b128 v[196:199], v179 offset:33792
	ds_read_b128 v[200:203], v179 offset:34816
	ds_read_b128 v[222:225], v179 offset:35840
	ds_read_b128 v[226:229], v179 offset:36864
	ds_read_b128 v[230:233], v179 offset:37888
	ds_read_b128 v[234:237], v179 offset:38912
	ds_read_b128 v[238:241], v179 offset:39936
	global_load_lds_dwordx4 v[242:243], off
	v_lshl_add_u64 v[242:243], s[28:29], 0, v[140:141]
	s_mov_b32 m0, s39
	s_nop 0
	global_load_lds_dwordx4 v[242:243], off
	s_waitcnt vmcnt(8)
	s_waitcnt lgkmcnt(0)
	s_barrier
	s_setprio 1
	s_waitcnt lgkmcnt(0)
	v_mfma_f32_16x16x32_bf16 v[124:127], v[128:131], v[192:195], v[124:127]
	v_mfma_f32_16x16x32_bf16 v[120:123], v[164:167], v[192:195], v[120:123]
	v_mfma_f32_16x16x32_bf16 v[108:111], v[128:131], v[200:203], v[108:111]
	v_mfma_f32_16x16x32_bf16 v[104:107], v[164:167], v[200:203], v[104:107]
	v_mfma_f32_16x16x32_bf16 v[92:95], v[128:131], v[226:229], v[92:95]
	v_mfma_f32_16x16x32_bf16 v[88:91], v[164:167], v[226:229], v[88:91]
	v_mfma_f32_16x16x32_bf16 v[76:79], v[128:131], v[234:237], v[76:79]
	v_mfma_f32_16x16x32_bf16 v[72:75], v[164:167], v[234:237], v[72:75]
	v_mfma_f32_16x16x32_bf16 v[124:127], v[132:135], v[196:199], v[124:127]
	v_mfma_f32_16x16x32_bf16 v[120:123], v[168:171], v[196:199], v[120:123]
	v_mfma_f32_16x16x32_bf16 v[108:111], v[132:135], v[222:225], v[108:111]
	v_mfma_f32_16x16x32_bf16 v[104:107], v[168:171], v[222:225], v[104:107]
	v_mfma_f32_16x16x32_bf16 v[92:95], v[132:135], v[230:233], v[92:95]
	v_mfma_f32_16x16x32_bf16 v[88:91], v[168:171], v[230:233], v[88:91]
	v_mfma_f32_16x16x32_bf16 v[76:79], v[132:135], v[238:241], v[76:79]
	v_mfma_f32_16x16x32_bf16 v[72:75], v[168:171], v[238:241], v[72:75]
	v_mfma_f32_16x16x32_bf16 v[116:119], v[172:175], v[192:195], v[116:119]
	v_mfma_f32_16x16x32_bf16 v[112:115], v[184:187], v[192:195], v[112:115]
	v_mfma_f32_16x16x32_bf16 v[100:103], v[172:175], v[200:203], v[100:103]
	v_mfma_f32_16x16x32_bf16 v[96:99], v[184:187], v[200:203], v[96:99]
	v_mfma_f32_16x16x32_bf16 v[84:87], v[172:175], v[226:229], v[84:87]
	v_mfma_f32_16x16x32_bf16 v[80:83], v[184:187], v[226:229], v[80:83]
	v_mfma_f32_16x16x32_bf16 v[68:71], v[172:175], v[234:237], v[68:71]
	v_mfma_f32_16x16x32_bf16 v[64:67], v[184:187], v[234:237], v[64:67]
	v_mfma_f32_16x16x32_bf16 v[116:119], v[180:183], v[196:199], v[116:119]
	v_mfma_f32_16x16x32_bf16 v[112:115], v[188:191], v[196:199], v[112:115]
	v_mfma_f32_16x16x32_bf16 v[100:103], v[180:183], v[222:225], v[100:103]
	v_mfma_f32_16x16x32_bf16 v[96:99], v[188:191], v[222:225], v[96:99]
	v_mfma_f32_16x16x32_bf16 v[84:87], v[180:183], v[230:233], v[84:87]
	v_mfma_f32_16x16x32_bf16 v[80:83], v[188:191], v[230:233], v[80:83]
	v_mfma_f32_16x16x32_bf16 v[68:71], v[180:183], v[238:241], v[68:71]
	v_mfma_f32_16x16x32_bf16 v[64:67], v[188:191], v[238:241], v[64:67]
	s_setprio 0
	s_barrier
; #define PG8_STAGE(bufoff, gbase, voff) do { _Pragma("unroll") for (int _i = 0; _i < 2; ++_i) \
;         __builtin_amdgcn_global_load_lds((const unsigned*)((const char*)(gbase) + (voff)[_i]), (PG8_LAS unsigned*)(lds + (bufoff) + ldsw + _i * 8192), 16, 0, 0); } while (0)
; #define PG8_LDA(dst, b, h) do { _Pragma("unroll") for (int m = 0; m < 4; ++m) _Pragma("unroll") for (int k = 0; k < 2; ++k) dst[m][k] = *(const PG8_LAS bf16x8*)(lds + PG8_SA(b, h) + aoff + m * 2048 + k * 1024); } while (0)
; #define PG8_MMA(ai, bj, At, Bt) do { __builtin_amdgcn_s_setprio(1); _Pragma("unroll") for (int m = 0; m < 4; ++m) _Pragma("unroll") for (int n = 0; n < 2; ++n) _Pragma("unroll") for (int k = 0; k < 2; ++k) \
;         acc[ai][bj][m][n] = __builtin_amdgcn_mfma_f32_16x16x32_bf16(Bt[n][k], At[m][k], acc[ai][bj][m][n], 0, 0, 0); __builtin_amdgcn_s_setprio(0); } while (0)
; #define PG8_WAIT_V(n) asm volatile("s_waitcnt vmcnt(" #n ")" ::: "memory")
; #define PG8_WAIT_L(n) asm volatile("s_waitcnt lgkmcnt(" #n ")" ::: "memory")
; #define PG8_BAR __builtin_amdgcn_s_barrier()
; #define PG8_SCHED __builtin_amdgcn_sched_barrier(0)
; template <class Epi, class Sched, bool ALIGN_EPI = false, bool SP2 = false>
; __device__ __forceinline__ void gemm_phase(PG8_LAS unsigned char* lds, const Gemm g, const Sched& S, const Epi& E, const int tid) {
;     ...
;         for (int t = 0; t < nt; t += 2) {
;             const bool last = (t == nt - 2);
;     ...
;             PG8_LDA(At, 1, 1); PG8_STAGE(PG8_SB(1, 0), b3, voffB); PG8_STAGE(PG8_SB(1, 1), b3 + hstep, voffB); PG8_STAGE(PG8_SA(1, 0), a3, voffA);
;             PG8_WAIT_V(8); PG8_WAIT_L(0); PG8_BAR; PG8_MMA(1, 0, At, B0); PG8_MMA(1, 1, At, B1); PG8_BAR; PG8_SCHED;
	s_add_i32 s28, s55, s35
	v_lshl_add_u64 v[150:151], v[150:151], 0, s[60:61]
	s_mov_b32 m0, s28
	ds_read_b128 v[192:195], v179 offset:49152
	ds_read_b128 v[196:199], v179 offset:50176
	ds_read_b128 v[200:203], v179 offset:51200
	ds_read_b128 v[222:225], v179 offset:52224
	ds_read_b128 v[226:229], v179 offset:53248
	ds_read_b128 v[230:233], v179 offset:54272
	ds_read_b128 v[234:237], v179 offset:55296
	ds_read_b128 v[238:241], v179 offset:56320
	global_load_lds_dwordx4 v[150:151], off
	s_add_i32 m0, s28, 0x2000
	s_add_u32 s26, s26, 0x40080
	v_lshl_add_u64 v[150:151], v[176:177], 0, s[60:61]
	s_addc_u32 s27, s27, 0
	s_add_i32 s28, s56, s35
	global_load_lds_dwordx4 v[150:151], off
	v_lshl_add_u64 v[150:151], s[26:27], 0, v[138:139]
	s_mov_b32 m0, s28
	s_nop 0
	global_load_lds_dwordx4 v[150:151], off
	v_lshl_add_u64 v[150:151], s[26:27], 0, v[142:143]
	s_add_i32 m0, s28, 0x2000
	s_nop 0
	global_load_lds_dwordx4 v[150:151], off
	v_lshl_add_u64 v[150:151], v[204:205], 0, s[60:61]
	s_mov_b32 m0, s45
	s_nop 0
	global_load_lds_dwordx4 v[150:151], off
	v_lshl_add_u64 v[150:151], v[206:207], 0, s[60:61]
	s_mov_b32 m0, s46
	s_nop 0
	global_load_lds_dwordx4 v[150:151], off
	s_waitcnt vmcnt(8)
	s_waitcnt lgkmcnt(0)
	s_barrier
	s_setprio 1
	s_waitcnt lgkmcnt(0)
	v_mfma_f32_16x16x32_bf16 v[60:63], v[128:131], v[192:195], v[60:63]
	v_mfma_f32_16x16x32_bf16 v[56:59], v[164:167], v[192:195], v[56:59]
	v_mfma_f32_16x16x32_bf16 v[44:47], v[128:131], v[200:203], v[44:47]
	v_mfma_f32_16x16x32_bf16 v[40:43], v[164:167], v[200:203], v[40:43]
	v_mfma_f32_16x16x32_bf16 v[28:31], v[128:131], v[226:229], v[28:31]
	v_mfma_f32_16x16x32_bf16 v[24:27], v[164:167], v[226:229], v[24:27]
	v_mfma_f32_16x16x32_bf16 v[12:15], v[128:131], v[234:237], v[12:15]
	v_mfma_f32_16x16x32_bf16 v[8:11], v[164:167], v[234:237], v[8:11]
	v_mfma_f32_16x16x32_bf16 v[60:63], v[132:135], v[196:199], v[60:63]
	v_mfma_f32_16x16x32_bf16 v[56:59], v[168:171], v[196:199], v[56:59]
	v_mfma_f32_16x16x32_bf16 v[44:47], v[132:135], v[222:225], v[44:47]
	v_mfma_f32_16x16x32_bf16 v[40:43], v[168:171], v[222:225], v[40:43]
	v_mfma_f32_16x16x32_bf16 v[28:31], v[132:135], v[230:233], v[28:31]
	v_mfma_f32_16x16x32_bf16 v[24:27], v[168:171], v[230:233], v[24:27]
	v_mfma_f32_16x16x32_bf16 v[12:15], v[132:135], v[238:241], v[12:15]
	v_mfma_f32_16x16x32_bf16 v[8:11], v[168:171], v[238:241], v[8:11]
	v_mfma_f32_16x16x32_bf16 v[52:55], v[172:175], v[192:195], v[52:55]
	v_mfma_f32_16x16x32_bf16 v[48:51], v[184:187], v[192:195], v[48:51]
	v_mfma_f32_16x16x32_bf16 v[36:39], v[172:175], v[200:203], v[36:39]
	v_mfma_f32_16x16x32_bf16 v[32:35], v[184:187], v[200:203], v[32:35]
	v_mfma_f32_16x16x32_bf16 v[20:23], v[172:175], v[226:229], v[20:23]
	v_mfma_f32_16x16x32_bf16 v[16:19], v[184:187], v[226:229], v[16:19]
	v_mfma_f32_16x16x32_bf16 v[4:7], v[172:175], v[234:237], v[4:7]
	v_mfma_f32_16x16x32_bf16 v[0:3], v[184:187], v[234:237], v[0:3]
	v_mfma_f32_16x16x32_bf16 v[52:55], v[180:183], v[196:199], v[52:55]
	v_mfma_f32_16x16x32_bf16 v[48:51], v[188:191], v[196:199], v[48:51]
	v_mfma_f32_16x16x32_bf16 v[36:39], v[180:183], v[222:225], v[36:39]
	v_mfma_f32_16x16x32_bf16 v[32:35], v[188:191], v[222:225], v[32:35]
	v_mfma_f32_16x16x32_bf16 v[20:23], v[180:183], v[230:233], v[20:23]
	v_mfma_f32_16x16x32_bf16 v[16:19], v[188:191], v[230:233], v[16:19]
	v_mfma_f32_16x16x32_bf16 v[4:7], v[180:183], v[238:241], v[4:7]
	v_mfma_f32_16x16x32_bf16 v[0:3], v[188:191], v[238:241], v[0:3]
	s_setprio 0
	s_barrier
	s_add_i32 s54, s54, 2
	s_add_u32 s2, s2, 0x100
	s_addc_u32 s3, s3, 0
	s_add_u32 s52, s52, 0x100
	s_addc_u32 s53, s53, 0
	s_cmp_gt_u32 s54, 13
	s_cbranch_scc0 .LBB0_126
	s_and_b64 vcc, exec, s[16:17]
	s_cbranch_vccz .LBB0_129
	s_barrier

; #define PG8_STAGE(bufoff, gbase, voff) do { _Pragma("unroll") for (int _i = 0; _i < 2; ++_i) \
;         __builtin_amdgcn_global_load_lds((const unsigned*)((const char*)(gbase) + (voff)[_i]), (PG8_LAS unsigned*)(lds + (bufoff) + ldsw + _i * 8192), 16, 0, 0); } while (0)
; #define PG8_LDA(dst, b, h) do { _Pragma("unroll") for (int m = 0; m < 4; ++m) _Pragma("unroll") for (int k = 0; k < 2; ++k) dst[m][k] = *(const PG8_LAS bf16x8*)(lds + PG8_SA(b, h) + aoff + m * 2048 + k * 1024); } while (0)
; #define PG8_LDB(dst, b, h) do { _Pragma("unroll") for (int n = 0; n < 2; ++n) _Pragma("unroll") for (int k = 0; k < 2; ++k) dst[n][k] = *(const PG8_LAS bf16x8*)(lds + PG8_SB(b, h) + boff + n * 2048 + k * 1024); } while (0)
; #define PG8_MMA(ai, bj, At, Bt) do { __builtin_amdgcn_s_setprio(1); _Pragma("unroll") for (int m = 0; m < 4; ++m) _Pragma("unroll") for (int n = 0; n < 2; ++n) _Pragma("unroll") for (int k = 0; k < 2; ++k) \
;         acc[ai][bj][m][n] = __builtin_amdgcn_mfma_f32_16x16x32_bf16(Bt[n][k], At[m][k], acc[ai][bj][m][n], 0, 0, 0); __builtin_amdgcn_s_setprio(0); } while (0)
; #define PG8_WAIT_V(n) asm volatile("s_waitcnt vmcnt(" #n ")" ::: "memory")
; #define PG8_WAIT_L(n) asm volatile("s_waitcnt lgkmcnt(" #n ")" ::: "memory")
; template <class Epi, class Sched, bool ALIGN_EPI = false, bool SP2 = false>
; __device__ __forceinline__ void gemm_phase(PG8_LAS unsigned char* lds, const Gemm g, const Sched& S, const Epi& E, const int tid) {
;     ...
;             const bool last = (t == nt - 2);
;             const char* a1 = cA + (size_t)(t + 1) * kstep;
;             const char* a2 = last ? nA : cA + (size_t)(t + 2) * kstep; const char* b2 = last ? nB : cB + (size_t)(t + 2) * kstep;
;             const char* a3 = a2 + kstep; const char* b3 = b2 + kstep;
;             if (last && has_next) S.a_ready(nxt);
;             if constexpr (SP2) {
;             PG8_LDB(B0, 0, 0); PG8_LDB(B1, 0, 1); PG8_SCHED; PG8_LDA(At, 0, 0); PG8_STAGE(PG8_SA(1, 1), a1 + hstep, voffA);
;             PG8_WAIT_V(8); PG8_WAIT_L(0); PG8_BAR; PG8_MMA(0, 0, At, B0); PG8_MMA(0, 1, At, B1); PG8_BAR; PG8_SCHED;
;             PG8_LDA(At, 0, 1); PG8_STAGE(PG8_SB(0, 0), b2, voffB); PG8_STAGE(PG8_SB(0, 1), b2 + hstep, voffB); PG8_STAGE(PG8_SA(0, 0), a2, voffA);
;             PG8_WAIT_V(8); PG8_WAIT_L(0); PG8_BAR; PG8_MMA(1, 0, At, B0); PG8_MMA(1, 1, At, B1); PG8_BAR; PG8_SCHED;
.LBB0_881:
	s_add_i32 s59, s34, 2
	s_add_u32 s60, s30, 0x80
	s_addc_u32 s35, s31, 0
	s_add_i32 s62, 0, 0x10000
	s_cmp_eq_u32 s52, s34
	s_cselect_b32 s35, s3, s35
	s_cselect_b32 s34, s2, s60
	v_add_u32_e32 v138, s62, v224
	s_cselect_b32 s61, s5, s58
	s_cselect_b32 s60, s4, s57
	s_add_i32 s63, 0, 0x14000
	ds_read_b128 v[154:157], v138
	ds_read_b128 v[158:161], v138 offset:1024
	ds_read_b128 v[162:165], v138 offset:2048
	ds_read_b128 v[166:169], v138 offset:3072
	v_add_u32_e32 v138, s63, v224
	ds_read_b128 v[170:173], v138
	ds_read_b128 v[174:177], v138 offset:1024
	ds_read_b128 v[178:181], v138 offset:2048
	ds_read_b128 v[182:185], v138 offset:3072
	v_lshl_add_u64 v[138:139], s[30:31], 0, v[134:135]
	s_add_i32 m0, s42, 0xc000
	ds_read_b128 v[186:189], v226
	ds_read_b128 v[190:193], v226 offset:1024
	ds_read_b128 v[194:197], v226 offset:2048
	ds_read_b128 v[198:201], v226 offset:3072
	ds_read_b128 v[202:205], v226 offset:4096
	ds_read_b128 v[228:231], v226 offset:5120
	ds_read_b128 v[232:235], v226 offset:6144
	ds_read_b128 v[236:239], v226 offset:7168
	global_load_lds_dwordx4 v[138:139], off
	v_lshl_add_u64 v[138:139], s[30:31], 0, v[136:137]
	s_add_i32 m0, s42, 0xe000
	s_nop 0
	global_load_lds_dwordx4 v[138:139], off
	s_waitcnt vmcnt(8)
	s_waitcnt lgkmcnt(0)
	s_barrier
	s_setprio 1
	s_waitcnt lgkmcnt(0)
	v_mfma_f32_16x16x32_bf16 v[124:127], v[154:157], v[186:189], v[124:127]
	v_mfma_f32_16x16x32_bf16 v[120:123], v[162:165], v[186:189], v[120:123]
	v_mfma_f32_16x16x32_bf16 v[116:119], v[154:157], v[194:197], v[116:119]
	v_mfma_f32_16x16x32_bf16 v[112:115], v[162:165], v[194:197], v[112:115]
	v_mfma_f32_16x16x32_bf16 v[108:111], v[154:157], v[202:205], v[108:111]
	v_mfma_f32_16x16x32_bf16 v[104:107], v[162:165], v[202:205], v[104:107]
	v_mfma_f32_16x16x32_bf16 v[100:103], v[154:157], v[232:235], v[100:103]
	v_mfma_f32_16x16x32_bf16 v[96:99], v[162:165], v[232:235], v[96:99]
	v_mfma_f32_16x16x32_bf16 v[124:127], v[158:161], v[190:193], v[124:127]
	v_mfma_f32_16x16x32_bf16 v[120:123], v[166:169], v[190:193], v[120:123]
	v_mfma_f32_16x16x32_bf16 v[116:119], v[158:161], v[198:201], v[116:119]
	v_mfma_f32_16x16x32_bf16 v[112:115], v[166:169], v[198:201], v[112:115]
	v_mfma_f32_16x16x32_bf16 v[108:111], v[158:161], v[228:231], v[108:111]
	v_mfma_f32_16x16x32_bf16 v[104:107], v[166:169], v[228:231], v[104:107]
	v_mfma_f32_16x16x32_bf16 v[100:103], v[158:161], v[236:239], v[100:103]
	v_mfma_f32_16x16x32_bf16 v[96:99], v[166:169], v[236:239], v[96:99]
	v_mfma_f32_16x16x32_bf16 v[60:63], v[170:173], v[186:189], v[60:63]
	v_mfma_f32_16x16x32_bf16 v[56:59], v[178:181], v[186:189], v[56:59]
	v_mfma_f32_16x16x32_bf16 v[52:55], v[170:173], v[194:197], v[52:55]
	v_mfma_f32_16x16x32_bf16 v[48:51], v[178:181], v[194:197], v[48:51]
	v_mfma_f32_16x16x32_bf16 v[44:47], v[170:173], v[202:205], v[44:47]
	v_mfma_f32_16x16x32_bf16 v[40:43], v[178:181], v[202:205], v[40:43]
	v_mfma_f32_16x16x32_bf16 v[36:39], v[170:173], v[232:235], v[36:39]
	v_mfma_f32_16x16x32_bf16 v[32:35], v[178:181], v[232:235], v[32:35]
	v_mfma_f32_16x16x32_bf16 v[60:63], v[174:177], v[190:193], v[60:63]
	v_mfma_f32_16x16x32_bf16 v[56:59], v[182:185], v[190:193], v[56:59]
	v_mfma_f32_16x16x32_bf16 v[52:55], v[174:177], v[198:201], v[52:55]
	v_mfma_f32_16x16x32_bf16 v[48:51], v[182:185], v[198:201], v[48:51]
	v_mfma_f32_16x16x32_bf16 v[44:47], v[174:177], v[228:231], v[44:47]
	v_mfma_f32_16x16x32_bf16 v[40:43], v[182:185], v[228:231], v[40:43]
	v_mfma_f32_16x16x32_bf16 v[36:39], v[174:177], v[236:239], v[36:39]
	v_mfma_f32_16x16x32_bf16 v[32:35], v[182:185], v[236:239], v[32:35]
	s_setprio 0
	s_barrier
	s_add_i32 s62, s62, s41
	v_lshl_add_u64 v[138:139], s[60:61], 0, v[146:147]
	s_mov_b32 m0, s62
	ds_read_b128 v[186:189], v226 offset:16384
	ds_read_b128 v[190:193], v226 offset:17408
	ds_read_b128 v[194:197], v226 offset:18432
	ds_read_b128 v[198:201], v226 offset:19456
	ds_read_b128 v[202:205], v226 offset:20480
	ds_read_b128 v[228:231], v226 offset:21504
	ds_read_b128 v[232:235], v226 offset:22528
	ds_read_b128 v[236:239], v226 offset:23552
	global_load_lds_dwordx4 v[138:139], off
	s_add_i32 m0, s62, 0x2000
	v_lshl_add_u64 v[142:143], s[60:61], 0, v[132:133]
	s_add_u32 s60, s60, s10
	s_addc_u32 s61, s61, 0
	s_add_i32 s62, s63, s41
	global_load_lds_dwordx4 v[142:143], off
	v_lshl_add_u64 v[240:241], s[60:61], 0, v[146:147]
	s_mov_b32 m0, s62
	v_lshl_add_u64 v[242:243], s[60:61], 0, v[132:133]
	global_load_lds_dwordx4 v[240:241], off
	s_add_i32 m0, s62, 0x2000
	v_lshl_add_u64 v[244:245], s[34:35], 0, v[128:129]
	global_load_lds_dwordx4 v[242:243], off
	s_mov_b32 m0, s42
	v_lshl_add_u64 v[246:247], s[34:35], 0, v[130:131]
	global_load_lds_dwordx4 v[244:245], off
	s_mov_b32 m0, s43
	s_nop 0
	global_load_lds_dwordx4 v[246:247], off
	s_waitcnt vmcnt(8)
	s_waitcnt lgkmcnt(0)
	s_barrier
; #define PG8_STAGE(bufoff, gbase, voff) do { _Pragma("unroll") for (int _i = 0; _i < 2; ++_i) \
;         __builtin_amdgcn_global_load_lds((const unsigned*)((const char*)(gbase) + (voff)[_i]), (PG8_LAS unsigned*)(lds + (bufoff) + ldsw + _i * 8192), 16, 0, 0); } while (0)
; #define PG8_LDA(dst, b, h) do { _Pragma("unroll") for (int m = 0; m < 4; ++m) _Pragma("unroll") for (int k = 0; k < 2; ++k) dst[m][k] = *(const PG8_LAS bf16x8*)(lds + PG8_SA(b, h) + aoff + m * 2048 + k * 1024); } while (0)
; #define PG8_LDB(dst, b, h) do { _Pragma("unroll") for (int n = 0; n < 2; ++n) _Pragma("unroll") for (int k = 0; k < 2; ++k) dst[n][k] = *(const PG8_LAS bf16x8*)(lds + PG8_SB(b, h) + boff + n * 2048 + k * 1024); } while (0)
; #define PG8_MMA(ai, bj, At, Bt) do { __builtin_amdgcn_s_setprio(1); _Pragma("unroll") for (int m = 0; m < 4; ++m) _Pragma("unroll") for (int n = 0; n < 2; ++n) _Pragma("unroll") for (int k = 0; k < 2; ++k) \
;         acc[ai][bj][m][n] = __builtin_amdgcn_mfma_f32_16x16x32_bf16(Bt[n][k], At[m][k], acc[ai][bj][m][n], 0, 0, 0); __builtin_amdgcn_s_setprio(0); } while (0)
; #define PG8_WAIT_V(n) asm volatile("s_waitcnt vmcnt(" #n ")" ::: "memory")
; #define PG8_WAIT_L(n) asm volatile("s_waitcnt lgkmcnt(" #n ")" ::: "memory")
; #define PG8_BAR __builtin_amdgcn_s_barrier()
; #define PG8_SCHED __builtin_amdgcn_sched_barrier(0)
; template <class Epi, class Sched, bool ALIGN_EPI = false, bool SP2 = false>
; __device__ __forceinline__ void gemm_phase(PG8_LAS unsigned char* lds, const Gemm g, const Sched& S, const Epi& E, const int tid) {
;     ...
;             PG8_WAIT_V(8); PG8_WAIT_L(0); PG8_BAR; PG8_MMA(1, 0, At, B0); PG8_MMA(1, 1, At, B1); PG8_BAR; PG8_SCHED;
;             PG8_LDB(B0, 1, 0); PG8_LDB(B1, 1, 1); PG8_SCHED; PG8_LDA(At, 1, 0); PG8_STAGE(PG8_SA(0, 1), a2 + hstep, voffA);
;             PG8_WAIT_V(8); PG8_WAIT_L(0); PG8_BAR; PG8_MMA(0, 0, At, B0); PG8_MMA(0, 1, At, B1); PG8_BAR; PG8_SCHED;
	s_setprio 1
	s_waitcnt lgkmcnt(0)
	v_mfma_f32_16x16x32_bf16 v[92:95], v[154:157], v[186:189], v[92:95]
	v_mfma_f32_16x16x32_bf16 v[88:91], v[162:165], v[186:189], v[88:91]
	v_mfma_f32_16x16x32_bf16 v[84:87], v[154:157], v[194:197], v[84:87]
	v_mfma_f32_16x16x32_bf16 v[80:83], v[162:165], v[194:197], v[80:83]
	v_mfma_f32_16x16x32_bf16 v[76:79], v[154:157], v[202:205], v[76:79]
	v_mfma_f32_16x16x32_bf16 v[72:75], v[162:165], v[202:205], v[72:75]
	v_mfma_f32_16x16x32_bf16 v[68:71], v[154:157], v[232:235], v[68:71]
	v_mfma_f32_16x16x32_bf16 v[64:67], v[162:165], v[232:235], v[64:67]
	v_mfma_f32_16x16x32_bf16 v[92:95], v[158:161], v[190:193], v[92:95]
	v_mfma_f32_16x16x32_bf16 v[88:91], v[166:169], v[190:193], v[88:91]
	v_mfma_f32_16x16x32_bf16 v[84:87], v[158:161], v[198:201], v[84:87]
	v_mfma_f32_16x16x32_bf16 v[80:83], v[166:169], v[198:201], v[80:83]
	v_mfma_f32_16x16x32_bf16 v[76:79], v[158:161], v[228:231], v[76:79]
	v_mfma_f32_16x16x32_bf16 v[72:75], v[166:169], v[228:231], v[72:75]
	v_mfma_f32_16x16x32_bf16 v[68:71], v[158:161], v[236:239], v[68:71]
	v_mfma_f32_16x16x32_bf16 v[64:67], v[166:169], v[236:239], v[64:67]
	v_mfma_f32_16x16x32_bf16 v[28:31], v[170:173], v[186:189], v[28:31]
	v_mfma_f32_16x16x32_bf16 v[24:27], v[178:181], v[186:189], v[24:27]
	v_mfma_f32_16x16x32_bf16 v[20:23], v[170:173], v[194:197], v[20:23]
	v_mfma_f32_16x16x32_bf16 v[16:19], v[178:181], v[194:197], v[16:19]
	v_mfma_f32_16x16x32_bf16 v[12:15], v[170:173], v[202:205], v[12:15]
	v_mfma_f32_16x16x32_bf16 v[8:11], v[178:181], v[202:205], v[8:11]
	v_mfma_f32_16x16x32_bf16 v[4:7], v[170:173], v[232:235], v[4:7]
	v_mfma_f32_16x16x32_bf16 v[0:3], v[178:181], v[232:235], v[0:3]
	v_mfma_f32_16x16x32_bf16 v[28:31], v[174:177], v[190:193], v[28:31]
	v_mfma_f32_16x16x32_bf16 v[24:27], v[182:185], v[190:193], v[24:27]
	v_mfma_f32_16x16x32_bf16 v[20:23], v[174:177], v[198:201], v[20:23]
	v_mfma_f32_16x16x32_bf16 v[16:19], v[182:185], v[198:201], v[16:19]
	v_mfma_f32_16x16x32_bf16 v[12:15], v[174:177], v[228:231], v[12:15]
	v_mfma_f32_16x16x32_bf16 v[8:11], v[182:185], v[228:231], v[8:11]
	v_mfma_f32_16x16x32_bf16 v[4:7], v[174:177], v[236:239], v[4:7]
	v_mfma_f32_16x16x32_bf16 v[0:3], v[182:185], v[236:239], v[0:3]
	s_setprio 0
	s_barrier
	s_add_i32 s60, 0, 0x18000
	v_add_u32_e32 v140, s60, v224
	s_add_i32 s61, 0, 0x1c000
	ds_read_b128 v[154:157], v140
	ds_read_b128 v[158:161], v140 offset:1024
	ds_read_b128 v[162:165], v140 offset:2048
	ds_read_b128 v[166:169], v140 offset:3072
	v_add_u32_e32 v140, s61, v224
	ds_read_b128 v[170:173], v140
	ds_read_b128 v[174:177], v140 offset:1024
	ds_read_b128 v[178:181], v140 offset:2048
	ds_read_b128 v[182:185], v140 offset:3072
	s_add_u32 s34, s34, s10
	s_addc_u32 s35, s35, 0
	s_mov_b32 m0, s44
	v_lshl_add_u64 v[248:249], s[34:35], 0, v[128:129]
	ds_read_b128 v[186:189], v226 offset:32768
	ds_read_b128 v[190:193], v226 offset:33792
	ds_read_b128 v[194:197], v226 offset:34816
	ds_read_b128 v[198:201], v226 offset:35840
	ds_read_b128 v[202:205], v226 offset:36864
	ds_read_b128 v[228:231], v226 offset:37888
	ds_read_b128 v[232:235], v226 offset:38912
	ds_read_b128 v[236:239], v226 offset:39936
	global_load_lds_dwordx4 v[248:249], off
	v_lshl_add_u64 v[248:249], s[34:35], 0, v[130:131]
	s_mov_b32 m0, s45
	s_nop 0
	global_load_lds_dwordx4 v[248:249], off
	s_waitcnt vmcnt(8)
	s_waitcnt lgkmcnt(0)
	s_barrier
	s_setprio 1
	s_waitcnt lgkmcnt(0)
	v_mfma_f32_16x16x32_bf16 v[124:127], v[154:157], v[186:189], v[124:127]
	v_mfma_f32_16x16x32_bf16 v[120:123], v[162:165], v[186:189], v[120:123]
	v_mfma_f32_16x16x32_bf16 v[116:119], v[154:157], v[194:197], v[116:119]
	v_mfma_f32_16x16x32_bf16 v[112:115], v[162:165], v[194:197], v[112:115]
	v_mfma_f32_16x16x32_bf16 v[108:111], v[154:157], v[202:205], v[108:111]
	v_mfma_f32_16x16x32_bf16 v[104:107], v[162:165], v[202:205], v[104:107]
	v_mfma_f32_16x16x32_bf16 v[100:103], v[154:157], v[232:235], v[100:103]
	v_mfma_f32_16x16x32_bf16 v[96:99], v[162:165], v[232:235], v[96:99]
	v_mfma_f32_16x16x32_bf16 v[124:127], v[158:161], v[190:193], v[124:127]
	v_mfma_f32_16x16x32_bf16 v[120:123], v[166:169], v[190:193], v[120:123]
	v_mfma_f32_16x16x32_bf16 v[116:119], v[158:161], v[198:201], v[116:119]
	v_mfma_f32_16x16x32_bf16 v[112:115], v[166:169], v[198:201], v[112:115]
	v_mfma_f32_16x16x32_bf16 v[108:111], v[158:161], v[228:231], v[108:111]
	v_mfma_f32_16x16x32_bf16 v[104:107], v[166:169], v[228:231], v[104:107]
	v_mfma_f32_16x16x32_bf16 v[100:103], v[158:161], v[236:239], v[100:103]
	v_mfma_f32_16x16x32_bf16 v[96:99], v[166:169], v[236:239], v[96:99]
	v_mfma_f32_16x16x32_bf16 v[60:63], v[170:173], v[186:189], v[60:63]
	v_mfma_f32_16x16x32_bf16 v[56:59], v[178:181], v[186:189], v[56:59]
	v_mfma_f32_16x16x32_bf16 v[52:55], v[170:173], v[194:197], v[52:55]
	v_mfma_f32_16x16x32_bf16 v[48:51], v[178:181], v[194:197], v[48:51]
	v_mfma_f32_16x16x32_bf16 v[44:47], v[170:173], v[202:205], v[44:47]
	v_mfma_f32_16x16x32_bf16 v[40:43], v[178:181], v[202:205], v[40:43]
	v_mfma_f32_16x16x32_bf16 v[36:39], v[170:173], v[232:235], v[36:39]
	v_mfma_f32_16x16x32_bf16 v[32:35], v[178:181], v[232:235], v[32:35]
	v_mfma_f32_16x16x32_bf16 v[60:63], v[174:177], v[190:193], v[60:63]
	v_mfma_f32_16x16x32_bf16 v[56:59], v[182:185], v[190:193], v[56:59]
	v_mfma_f32_16x16x32_bf16 v[52:55], v[174:177], v[198:201], v[52:55]
	v_mfma_f32_16x16x32_bf16 v[48:51], v[182:185], v[198:201], v[48:51]
	v_mfma_f32_16x16x32_bf16 v[44:47], v[174:177], v[228:231], v[44:47]
	v_mfma_f32_16x16x32_bf16 v[40:43], v[182:185], v[228:231], v[40:43]
	v_mfma_f32_16x16x32_bf16 v[36:39], v[174:177], v[236:239], v[36:39]
	v_mfma_f32_16x16x32_bf16 v[32:35], v[182:185], v[236:239], v[32:35]
	s_setprio 0
	s_barrier
; #define PG8_STAGE(bufoff, gbase, voff) do { _Pragma("unroll") for (int _i = 0; _i < 2; ++_i) \
;         __builtin_amdgcn_global_load_lds((const unsigned*)((const char*)(gbase) + (voff)[_i]), (PG8_LAS unsigned*)(lds + (bufoff) + ldsw + _i * 8192), 16, 0, 0); } while (0)
; #define PG8_LDA(dst, b, h) do { _Pragma("unroll") for (int m = 0; m < 4; ++m) _Pragma("unroll") for (int k = 0; k < 2; ++k) dst[m][k] = *(const PG8_LAS bf16x8*)(lds + PG8_SA(b, h) + aoff + m * 2048 + k * 1024); } while (0)
; #define PG8_MMA(ai, bj, At, Bt) do { __builtin_amdgcn_s_setprio(1); _Pragma("unroll") for (int m = 0; m < 4; ++m) _Pragma("unroll") for (int n = 0; n < 2; ++n) _Pragma("unroll") for (int k = 0; k < 2; ++k) \
;         acc[ai][bj][m][n] = __builtin_amdgcn_mfma_f32_16x16x32_bf16(Bt[n][k], At[m][k], acc[ai][bj][m][n], 0, 0, 0); __builtin_amdgcn_s_setprio(0); } while (0)
; #define PG8_WAIT_V(n) asm volatile("s_waitcnt vmcnt(" #n ")" ::: "memory")
; #define PG8_WAIT_L(n) asm volatile("s_waitcnt lgkmcnt(" #n ")" ::: "memory")
; #define PG8_BAR __builtin_amdgcn_s_barrier()
; #define PG8_SCHED __builtin_amdgcn_sched_barrier(0)
; template <class Epi, class Sched, bool ALIGN_EPI = false, bool SP2 = false>
; __device__ __forceinline__ void gemm_phase(PG8_LAS unsigned char* lds, const Gemm g, const Sched& S, const Epi& E, const int tid) {
;     ...
;         for (int t = 0; t < nt; t += 2) {
;             const bool last = (t == nt - 2);
;     ...
;             PG8_LDA(At, 1, 1); PG8_STAGE(PG8_SB(1, 0), b3, voffB); PG8_STAGE(PG8_SB(1, 1), b3 + hstep, voffB); PG8_STAGE(PG8_SA(1, 0), a3, voffA);
;             PG8_WAIT_V(8); PG8_WAIT_L(0); PG8_BAR; PG8_MMA(1, 0, At, B0); PG8_MMA(1, 1, At, B1); PG8_BAR; PG8_SCHED;
	s_add_i32 s34, s60, s41
	v_lshl_add_u64 v[138:139], v[138:139], 0, s[68:69]
	s_mov_b32 m0, s34
	ds_read_b128 v[186:189], v226 offset:49152
	ds_read_b128 v[190:193], v226 offset:50176
	ds_read_b128 v[194:197], v226 offset:51200
	ds_read_b128 v[198:201], v226 offset:52224
	ds_read_b128 v[202:205], v226 offset:53248
	ds_read_b128 v[228:231], v226 offset:54272
	ds_read_b128 v[232:235], v226 offset:55296
	ds_read_b128 v[236:239], v226 offset:56320
	global_load_lds_dwordx4 v[138:139], off
	v_lshl_add_u64 v[138:139], v[142:143], 0, s[68:69]
	s_add_i32 m0, s34, 0x2000
	s_add_i32 s34, s61, s41
	global_load_lds_dwordx4 v[138:139], off
	v_lshl_add_u64 v[138:139], v[240:241], 0, s[68:69]
	s_mov_b32 m0, s34
	s_nop 0
	global_load_lds_dwordx4 v[138:139], off
	v_lshl_add_u64 v[138:139], v[242:243], 0, s[68:69]
	s_add_i32 m0, s34, 0x2000
	s_nop 0
	global_load_lds_dwordx4 v[138:139], off
	v_lshl_add_u64 v[138:139], v[244:245], 0, s[68:69]
	s_mov_b32 m0, s48
	s_nop 0
	global_load_lds_dwordx4 v[138:139], off
	v_lshl_add_u64 v[138:139], v[246:247], 0, s[68:69]
	s_mov_b32 m0, s49
	s_nop 0
	global_load_lds_dwordx4 v[138:139], off
	s_waitcnt vmcnt(8)
	s_waitcnt lgkmcnt(0)
	s_barrier
	s_setprio 1
	s_waitcnt lgkmcnt(0)
	v_mfma_f32_16x16x32_bf16 v[92:95], v[154:157], v[186:189], v[92:95]
	v_mfma_f32_16x16x32_bf16 v[88:91], v[162:165], v[186:189], v[88:91]
	v_mfma_f32_16x16x32_bf16 v[84:87], v[154:157], v[194:197], v[84:87]
	v_mfma_f32_16x16x32_bf16 v[80:83], v[162:165], v[194:197], v[80:83]
	v_mfma_f32_16x16x32_bf16 v[76:79], v[154:157], v[202:205], v[76:79]
	v_mfma_f32_16x16x32_bf16 v[72:75], v[162:165], v[202:205], v[72:75]
	v_mfma_f32_16x16x32_bf16 v[68:71], v[154:157], v[232:235], v[68:71]
	v_mfma_f32_16x16x32_bf16 v[64:67], v[162:165], v[232:235], v[64:67]
	v_mfma_f32_16x16x32_bf16 v[92:95], v[158:161], v[190:193], v[92:95]
	v_mfma_f32_16x16x32_bf16 v[88:91], v[166:169], v[190:193], v[88:91]
	v_mfma_f32_16x16x32_bf16 v[84:87], v[158:161], v[198:201], v[84:87]
	v_mfma_f32_16x16x32_bf16 v[80:83], v[166:169], v[198:201], v[80:83]
	v_mfma_f32_16x16x32_bf16 v[76:79], v[158:161], v[228:231], v[76:79]
	v_mfma_f32_16x16x32_bf16 v[72:75], v[166:169], v[228:231], v[72:75]
	v_mfma_f32_16x16x32_bf16 v[68:71], v[158:161], v[236:239], v[68:71]
	v_mfma_f32_16x16x32_bf16 v[64:67], v[166:169], v[236:239], v[64:67]
	v_mfma_f32_16x16x32_bf16 v[28:31], v[170:173], v[186:189], v[28:31]
	v_mfma_f32_16x16x32_bf16 v[24:27], v[178:181], v[186:189], v[24:27]
	v_mfma_f32_16x16x32_bf16 v[20:23], v[170:173], v[194:197], v[20:23]
	v_mfma_f32_16x16x32_bf16 v[16:19], v[178:181], v[194:197], v[16:19]
	v_mfma_f32_16x16x32_bf16 v[12:15], v[170:173], v[202:205], v[12:15]
	v_mfma_f32_16x16x32_bf16 v[8:11], v[178:181], v[202:205], v[8:11]
	v_mfma_f32_16x16x32_bf16 v[4:7], v[170:173], v[232:235], v[4:7]
	v_mfma_f32_16x16x32_bf16 v[0:3], v[178:181], v[232:235], v[0:3]
	v_mfma_f32_16x16x32_bf16 v[28:31], v[174:177], v[190:193], v[28:31]
	v_mfma_f32_16x16x32_bf16 v[24:27], v[182:185], v[190:193], v[24:27]
	v_mfma_f32_16x16x32_bf16 v[20:23], v[174:177], v[198:201], v[20:23]
	v_mfma_f32_16x16x32_bf16 v[16:19], v[182:185], v[198:201], v[16:19]
	v_mfma_f32_16x16x32_bf16 v[12:15], v[174:177], v[228:231], v[12:15]
	v_mfma_f32_16x16x32_bf16 v[8:11], v[182:185], v[228:231], v[8:11]
	v_mfma_f32_16x16x32_bf16 v[4:7], v[174:177], v[236:239], v[4:7]
	v_mfma_f32_16x16x32_bf16 v[0:3], v[182:185], v[236:239], v[0:3]
	s_setprio 0
	s_barrier
	s_add_u32 s30, s30, 0x100
	s_addc_u32 s31, s31, 0
	s_add_u32 s57, s57, 0x100
	s_addc_u32 s58, s58, 0
	s_cmp_ge_u32 s59, s51
	s_mov_b32 s34, s59
	s_cbranch_scc0 .LBB0_881
	s_and_b64 vcc, exec, s[28:29]
	s_cbranch_vccz .LBB0_884
	s_barrier

; #define PG8_STAGE(bufoff, gbase, voff) do { _Pragma("unroll") for (int _i = 0; _i < 2; ++_i) \
;         __builtin_amdgcn_global_load_lds((const unsigned*)((const char*)(gbase) + (voff)[_i]), (PG8_LAS unsigned*)(lds + (bufoff) + ldsw + _i * 8192), 16, 0, 0); } while (0)
; #define PG8_LDA(dst, b, h) do { _Pragma("unroll") for (int m = 0; m < 4; ++m) _Pragma("unroll") for (int k = 0; k < 2; ++k) dst[m][k] = *(const PG8_LAS bf16x8*)(lds + PG8_SA(b, h) + aoff + m * 2048 + k * 1024); } while (0)
; #define PG8_LDB(dst, b, h) do { _Pragma("unroll") for (int n = 0; n < 2; ++n) _Pragma("unroll") for (int k = 0; k < 2; ++k) dst[n][k] = *(const PG8_LAS bf16x8*)(lds + PG8_SB(b, h) + boff + n * 2048 + k * 1024); } while (0)
; #define PG8_MMA(ai, bj, At, Bt) do { __builtin_amdgcn_s_setprio(1); _Pragma("unroll") for (int m = 0; m < 4; ++m) _Pragma("unroll") for (int n = 0; n < 2; ++n) _Pragma("unroll") for (int k = 0; k < 2; ++k) \
;         acc[ai][bj][m][n] = __builtin_amdgcn_mfma_f32_16x16x32_bf16(Bt[n][k], At[m][k], acc[ai][bj][m][n], 0, 0, 0); __builtin_amdgcn_s_setprio(0); } while (0)
; #define PG8_WAIT_V(n) asm volatile("s_waitcnt vmcnt(" #n ")" ::: "memory")
; #define PG8_WAIT_L(n) asm volatile("s_waitcnt lgkmcnt(" #n ")" ::: "memory")
; template <class Epi, class Sched, bool ALIGN_EPI = false, bool SP2 = false>
; __device__ __forceinline__ void gemm_phase(PG8_LAS unsigned char* lds, const Gemm g, const Sched& S, const Epi& E, const int tid) {
;     ...
;             const bool last = (t == nt - 2);
;             const char* a1 = cA + (size_t)(t + 1) * kstep;
;             const char* a2 = last ? nA : cA + (size_t)(t + 2) * kstep; const char* b2 = last ? nB : cB + (size_t)(t + 2) * kstep;
;             const char* a3 = a2 + kstep; const char* b3 = b2 + kstep;
;             if (last && has_next) S.a_ready(nxt);
;             if constexpr (SP2) {
;             PG8_LDB(B0, 0, 0); PG8_LDB(B1, 0, 1); PG8_SCHED; PG8_LDA(At, 0, 0); PG8_STAGE(PG8_SA(1, 1), a1 + hstep, voffA);
;             PG8_WAIT_V(8); PG8_WAIT_L(0); PG8_BAR; PG8_MMA(0, 0, At, B0); PG8_MMA(0, 1, At, B1); PG8_BAR; PG8_SCHED;
;             PG8_LDA(At, 0, 1); PG8_STAGE(PG8_SB(0, 0), b2, voffB); PG8_STAGE(PG8_SB(0, 1), b2 + hstep, voffB); PG8_STAGE(PG8_SA(0, 0), a2, voffA);
;             PG8_WAIT_V(8); PG8_WAIT_L(0); PG8_BAR; PG8_MMA(1, 0, At, B0); PG8_MMA(1, 1, At, B1); PG8_BAR; PG8_SCHED;
.LBB0_907:
	s_add_i32 s12, s14, 2
	s_mov_b32 s13, s41
	s_or_b32 s40, s14, 1
	s_lshl_b64 s[30:31], s[12:13], 7
	s_cmp_lg_u32 s14, s29
	s_cselect_b32 s30, s30, 0
	s_cselect_b32 s13, s31, 0
	s_add_u32 s14, s2, s30
	s_addc_u32 s15, s3, s13
	s_add_i32 s33, 0, 0x10000
	s_add_u32 s30, s0, s30
	v_add_u32_e32 v140, s33, v134
	s_addc_u32 s31, s1, s13
	s_add_i32 s13, 0, 0x14000
	ds_read_b128 v[136:139], v140
	ds_read_b128 v[154:157], v140 offset:1024
	ds_read_b128 v[158:161], v140 offset:2048
	ds_read_b128 v[162:165], v140 offset:3072
	v_add_u32_e32 v140, s13, v134
	ds_read_b128 v[166:169], v140
	ds_read_b128 v[170:173], v140 offset:1024
	ds_read_b128 v[174:177], v140 offset:2048
	ds_read_b128 v[178:181], v140 offset:3072
	s_lshl_b64 s[34:35], s[40:41], 7
	s_add_u32 s34, s4, s34
	s_addc_u32 s35, s5, s35
	v_lshl_add_u64 v[142:143], s[34:35], 0, v[128:129]
	s_add_i32 m0, s21, 0xc000
	ds_read_b128 v[182:185], v135
	ds_read_b128 v[186:189], v135 offset:1024
	ds_read_b128 v[190:193], v135 offset:2048
	ds_read_b128 v[194:197], v135 offset:3072
	ds_read_b128 v[198:201], v135 offset:4096
	ds_read_b128 v[202:205], v135 offset:5120
	ds_read_b128 v[222:225], v135 offset:6144
	ds_read_b128 v[226:229], v135 offset:7168
	global_load_lds_dwordx4 v[142:143], off
	v_lshl_add_u64 v[142:143], s[34:35], 0, v[130:131]
	s_add_i32 m0, s21, 0xe000
	s_nop 0
	global_load_lds_dwordx4 v[142:143], off
	s_waitcnt vmcnt(8)
	s_waitcnt lgkmcnt(0)
	s_barrier
	s_setprio 1
	s_waitcnt lgkmcnt(0)
	v_mfma_f32_16x16x32_bf16 v[120:123], v[136:139], v[182:185], v[120:123]
	v_mfma_f32_16x16x32_bf16 v[124:127], v[158:161], v[182:185], v[124:127]
	v_mfma_f32_16x16x32_bf16 v[112:115], v[136:139], v[190:193], v[112:115]
	v_mfma_f32_16x16x32_bf16 v[104:107], v[158:161], v[190:193], v[104:107]
	v_mfma_f32_16x16x32_bf16 v[96:99], v[136:139], v[198:201], v[96:99]
	v_mfma_f32_16x16x32_bf16 v[88:91], v[158:161], v[198:201], v[88:91]
	v_mfma_f32_16x16x32_bf16 v[80:83], v[136:139], v[222:225], v[80:83]
	v_mfma_f32_16x16x32_bf16 v[72:75], v[158:161], v[222:225], v[72:75]
	v_mfma_f32_16x16x32_bf16 v[120:123], v[154:157], v[186:189], v[120:123]
	v_mfma_f32_16x16x32_bf16 v[124:127], v[162:165], v[186:189], v[124:127]
	v_mfma_f32_16x16x32_bf16 v[112:115], v[154:157], v[194:197], v[112:115]
	v_mfma_f32_16x16x32_bf16 v[104:107], v[162:165], v[194:197], v[104:107]
	v_mfma_f32_16x16x32_bf16 v[96:99], v[154:157], v[202:205], v[96:99]
	v_mfma_f32_16x16x32_bf16 v[88:91], v[162:165], v[202:205], v[88:91]
	v_mfma_f32_16x16x32_bf16 v[80:83], v[154:157], v[226:229], v[80:83]
	v_mfma_f32_16x16x32_bf16 v[72:75], v[162:165], v[226:229], v[72:75]
	v_mfma_f32_16x16x32_bf16 v[116:119], v[166:169], v[182:185], v[116:119]
	v_mfma_f32_16x16x32_bf16 v[108:111], v[174:177], v[182:185], v[108:111]
	v_mfma_f32_16x16x32_bf16 v[100:103], v[166:169], v[190:193], v[100:103]
	v_mfma_f32_16x16x32_bf16 v[92:95], v[174:177], v[190:193], v[92:95]
	v_mfma_f32_16x16x32_bf16 v[84:87], v[166:169], v[198:201], v[84:87]
	v_mfma_f32_16x16x32_bf16 v[76:79], v[174:177], v[198:201], v[76:79]
	v_mfma_f32_16x16x32_bf16 v[68:71], v[166:169], v[222:225], v[68:71]
	v_mfma_f32_16x16x32_bf16 v[64:67], v[174:177], v[222:225], v[64:67]
	v_mfma_f32_16x16x32_bf16 v[116:119], v[170:173], v[186:189], v[116:119]
	v_mfma_f32_16x16x32_bf16 v[108:111], v[178:181], v[186:189], v[108:111]
	v_mfma_f32_16x16x32_bf16 v[100:103], v[170:173], v[194:197], v[100:103]
	v_mfma_f32_16x16x32_bf16 v[92:95], v[178:181], v[194:197], v[92:95]
	v_mfma_f32_16x16x32_bf16 v[84:87], v[170:173], v[202:205], v[84:87]
	v_mfma_f32_16x16x32_bf16 v[76:79], v[178:181], v[202:205], v[76:79]
	v_mfma_f32_16x16x32_bf16 v[68:71], v[170:173], v[226:229], v[68:71]
	v_mfma_f32_16x16x32_bf16 v[64:67], v[178:181], v[226:229], v[64:67]
	s_setprio 0
	s_barrier
	s_add_i32 s33, s33, s19
	v_lshl_add_u64 v[142:143], s[30:31], 0, v[146:147]
	s_mov_b32 m0, s33
	ds_read_b128 v[182:185], v135 offset:16384
	ds_read_b128 v[186:189], v135 offset:17408
	ds_read_b128 v[190:193], v135 offset:18432
	ds_read_b128 v[194:197], v135 offset:19456
	ds_read_b128 v[198:201], v135 offset:20480
	ds_read_b128 v[202:205], v135 offset:21504
	ds_read_b128 v[222:225], v135 offset:22528
	ds_read_b128 v[226:229], v135 offset:23552
	global_load_lds_dwordx4 v[142:143], off
	s_add_i32 m0, s33, 0x2000
	v_lshl_add_u64 v[150:151], s[30:31], 0, v[132:133]
	s_add_u32 s30, s30, s10
	s_addc_u32 s31, s31, 0
	s_add_i32 s13, s13, s19
	global_load_lds_dwordx4 v[150:151], off
	v_lshl_add_u64 v[206:207], s[30:31], 0, v[146:147]
	s_mov_b32 m0, s13
	v_lshl_add_u64 v[230:231], s[30:31], 0, v[132:133]
	global_load_lds_dwordx4 v[206:207], off
	s_add_i32 m0, s13, 0x2000
	v_lshl_add_u64 v[232:233], s[14:15], 0, v[128:129]
	global_load_lds_dwordx4 v[230:231], off
	s_mov_b32 m0, s21
	v_lshl_add_u64 v[234:235], s[14:15], 0, v[130:131]
	global_load_lds_dwordx4 v[232:233], off
	s_mov_b32 m0, s22
	s_nop 0
	global_load_lds_dwordx4 v[234:235], off
	s_waitcnt vmcnt(8)
	s_waitcnt lgkmcnt(0)
	s_barrier
; #define PG8_STAGE(bufoff, gbase, voff) do { _Pragma("unroll") for (int _i = 0; _i < 2; ++_i) \
;         __builtin_amdgcn_global_load_lds((const unsigned*)((const char*)(gbase) + (voff)[_i]), (PG8_LAS unsigned*)(lds + (bufoff) + ldsw + _i * 8192), 16, 0, 0); } while (0)
; #define PG8_LDA(dst, b, h) do { _Pragma("unroll") for (int m = 0; m < 4; ++m) _Pragma("unroll") for (int k = 0; k < 2; ++k) dst[m][k] = *(const PG8_LAS bf16x8*)(lds + PG8_SA(b, h) + aoff + m * 2048 + k * 1024); } while (0)
; #define PG8_LDB(dst, b, h) do { _Pragma("unroll") for (int n = 0; n < 2; ++n) _Pragma("unroll") for (int k = 0; k < 2; ++k) dst[n][k] = *(const PG8_LAS bf16x8*)(lds + PG8_SB(b, h) + boff + n * 2048 + k * 1024); } while (0)
; #define PG8_MMA(ai, bj, At, Bt) do { __builtin_amdgcn_s_setprio(1); _Pragma("unroll") for (int m = 0; m < 4; ++m) _Pragma("unroll") for (int n = 0; n < 2; ++n) _Pragma("unroll") for (int k = 0; k < 2; ++k) \
;         acc[ai][bj][m][n] = __builtin_amdgcn_mfma_f32_16x16x32_bf16(Bt[n][k], At[m][k], acc[ai][bj][m][n], 0, 0, 0); __builtin_amdgcn_s_setprio(0); } while (0)
; #define PG8_WAIT_V(n) asm volatile("s_waitcnt vmcnt(" #n ")" ::: "memory")
; #define PG8_WAIT_L(n) asm volatile("s_waitcnt lgkmcnt(" #n ")" ::: "memory")
; #define PG8_BAR __builtin_amdgcn_s_barrier()
; #define PG8_SCHED __builtin_amdgcn_sched_barrier(0)
; template <class Epi, class Sched, bool ALIGN_EPI = false, bool SP2 = false>
; __device__ __forceinline__ void gemm_phase(PG8_LAS unsigned char* lds, const Gemm g, const Sched& S, const Epi& E, const int tid) {
;     ...
;             PG8_WAIT_V(8); PG8_WAIT_L(0); PG8_BAR; PG8_MMA(1, 0, At, B0); PG8_MMA(1, 1, At, B1); PG8_BAR; PG8_SCHED;
;             PG8_LDB(B0, 1, 0); PG8_LDB(B1, 1, 1); PG8_SCHED; PG8_LDA(At, 1, 0); PG8_STAGE(PG8_SA(0, 1), a2 + hstep, voffA);
;             PG8_WAIT_V(8); PG8_WAIT_L(0); PG8_BAR; PG8_MMA(0, 0, At, B0); PG8_MMA(0, 1, At, B1); PG8_BAR; PG8_SCHED;
	s_setprio 1
	s_waitcnt lgkmcnt(0)
	v_mfma_f32_16x16x32_bf16 v[60:63], v[136:139], v[182:185], v[60:63]
	v_mfma_f32_16x16x32_bf16 v[56:59], v[158:161], v[182:185], v[56:59]
	v_mfma_f32_16x16x32_bf16 v[52:55], v[136:139], v[190:193], v[52:55]
	v_mfma_f32_16x16x32_bf16 v[40:43], v[158:161], v[190:193], v[40:43]
	v_mfma_f32_16x16x32_bf16 v[36:39], v[136:139], v[198:201], v[36:39]
	v_mfma_f32_16x16x32_bf16 v[24:27], v[158:161], v[198:201], v[24:27]
	v_mfma_f32_16x16x32_bf16 v[20:23], v[136:139], v[222:225], v[20:23]
	v_mfma_f32_16x16x32_bf16 v[8:11], v[158:161], v[222:225], v[8:11]
	v_mfma_f32_16x16x32_bf16 v[60:63], v[154:157], v[186:189], v[60:63]
	v_mfma_f32_16x16x32_bf16 v[56:59], v[162:165], v[186:189], v[56:59]
	v_mfma_f32_16x16x32_bf16 v[52:55], v[154:157], v[194:197], v[52:55]
	v_mfma_f32_16x16x32_bf16 v[40:43], v[162:165], v[194:197], v[40:43]
	v_mfma_f32_16x16x32_bf16 v[36:39], v[154:157], v[202:205], v[36:39]
	v_mfma_f32_16x16x32_bf16 v[24:27], v[162:165], v[202:205], v[24:27]
	v_mfma_f32_16x16x32_bf16 v[20:23], v[154:157], v[226:229], v[20:23]
	v_mfma_f32_16x16x32_bf16 v[8:11], v[162:165], v[226:229], v[8:11]
	v_mfma_f32_16x16x32_bf16 v[48:51], v[166:169], v[182:185], v[48:51]
	v_mfma_f32_16x16x32_bf16 v[44:47], v[174:177], v[182:185], v[44:47]
	v_mfma_f32_16x16x32_bf16 v[32:35], v[166:169], v[190:193], v[32:35]
	v_mfma_f32_16x16x32_bf16 v[28:31], v[174:177], v[190:193], v[28:31]
	v_mfma_f32_16x16x32_bf16 v[16:19], v[166:169], v[198:201], v[16:19]
	v_mfma_f32_16x16x32_bf16 v[12:15], v[174:177], v[198:201], v[12:15]
	v_mfma_f32_16x16x32_bf16 v[4:7], v[166:169], v[222:225], v[4:7]
	v_mfma_f32_16x16x32_bf16 v[0:3], v[174:177], v[222:225], v[0:3]
	v_mfma_f32_16x16x32_bf16 v[48:51], v[170:173], v[186:189], v[48:51]
	v_mfma_f32_16x16x32_bf16 v[44:47], v[178:181], v[186:189], v[44:47]
	v_mfma_f32_16x16x32_bf16 v[32:35], v[170:173], v[194:197], v[32:35]
	v_mfma_f32_16x16x32_bf16 v[28:31], v[178:181], v[194:197], v[28:31]
	v_mfma_f32_16x16x32_bf16 v[16:19], v[170:173], v[202:205], v[16:19]
	v_mfma_f32_16x16x32_bf16 v[12:15], v[178:181], v[202:205], v[12:15]
	v_mfma_f32_16x16x32_bf16 v[4:7], v[170:173], v[226:229], v[4:7]
	v_mfma_f32_16x16x32_bf16 v[0:3], v[178:181], v[226:229], v[0:3]
	s_setprio 0
	s_barrier
	s_add_i32 s13, 0, 0x18000
	v_add_u32_e32 v140, s13, v134
	s_add_i32 s30, 0, 0x1c000
	ds_read_b128 v[136:139], v140
	ds_read_b128 v[154:157], v140 offset:1024
	ds_read_b128 v[158:161], v140 offset:2048
	ds_read_b128 v[162:165], v140 offset:3072
	v_add_u32_e32 v140, s30, v134
	ds_read_b128 v[166:169], v140
	ds_read_b128 v[170:173], v140 offset:1024
	ds_read_b128 v[174:177], v140 offset:2048
	ds_read_b128 v[178:181], v140 offset:3072
	s_add_u32 s14, s14, s10
	s_addc_u32 s15, s15, 0
	s_mov_b32 m0, s23
	v_lshl_add_u64 v[236:237], s[14:15], 0, v[128:129]
	ds_read_b128 v[182:185], v135 offset:32768
	ds_read_b128 v[186:189], v135 offset:33792
	ds_read_b128 v[190:193], v135 offset:34816
	ds_read_b128 v[194:197], v135 offset:35840
	ds_read_b128 v[198:201], v135 offset:36864
	ds_read_b128 v[202:205], v135 offset:37888
	ds_read_b128 v[222:225], v135 offset:38912
	ds_read_b128 v[226:229], v135 offset:39936
	global_load_lds_dwordx4 v[236:237], off
	v_lshl_add_u64 v[236:237], s[14:15], 0, v[130:131]
	s_mov_b32 m0, s24
	s_nop 0
	global_load_lds_dwordx4 v[236:237], off
	s_waitcnt vmcnt(8)
	s_waitcnt lgkmcnt(0)
	s_barrier
	s_setprio 1
	s_waitcnt lgkmcnt(0)
	v_mfma_f32_16x16x32_bf16 v[120:123], v[136:139], v[182:185], v[120:123]
	v_mfma_f32_16x16x32_bf16 v[124:127], v[158:161], v[182:185], v[124:127]
	v_mfma_f32_16x16x32_bf16 v[112:115], v[136:139], v[190:193], v[112:115]
	v_mfma_f32_16x16x32_bf16 v[104:107], v[158:161], v[190:193], v[104:107]
	v_mfma_f32_16x16x32_bf16 v[96:99], v[136:139], v[198:201], v[96:99]
	v_mfma_f32_16x16x32_bf16 v[88:91], v[158:161], v[198:201], v[88:91]
	v_mfma_f32_16x16x32_bf16 v[80:83], v[136:139], v[222:225], v[80:83]
	v_mfma_f32_16x16x32_bf16 v[72:75], v[158:161], v[222:225], v[72:75]
	v_mfma_f32_16x16x32_bf16 v[120:123], v[154:157], v[186:189], v[120:123]
	v_mfma_f32_16x16x32_bf16 v[124:127], v[162:165], v[186:189], v[124:127]
	v_mfma_f32_16x16x32_bf16 v[112:115], v[154:157], v[194:197], v[112:115]
	v_mfma_f32_16x16x32_bf16 v[104:107], v[162:165], v[194:197], v[104:107]
	v_mfma_f32_16x16x32_bf16 v[96:99], v[154:157], v[202:205], v[96:99]
	v_mfma_f32_16x16x32_bf16 v[88:91], v[162:165], v[202:205], v[88:91]
	v_mfma_f32_16x16x32_bf16 v[80:83], v[154:157], v[226:229], v[80:83]
	v_mfma_f32_16x16x32_bf16 v[72:75], v[162:165], v[226:229], v[72:75]
	v_mfma_f32_16x16x32_bf16 v[116:119], v[166:169], v[182:185], v[116:119]
	v_mfma_f32_16x16x32_bf16 v[108:111], v[174:177], v[182:185], v[108:111]
	v_mfma_f32_16x16x32_bf16 v[100:103], v[166:169], v[190:193], v[100:103]
	v_mfma_f32_16x16x32_bf16 v[92:95], v[174:177], v[190:193], v[92:95]
	v_mfma_f32_16x16x32_bf16 v[84:87], v[166:169], v[198:201], v[84:87]
	v_mfma_f32_16x16x32_bf16 v[76:79], v[174:177], v[198:201], v[76:79]
	v_mfma_f32_16x16x32_bf16 v[68:71], v[166:169], v[222:225], v[68:71]
	v_mfma_f32_16x16x32_bf16 v[64:67], v[174:177], v[222:225], v[64:67]
	v_mfma_f32_16x16x32_bf16 v[116:119], v[170:173], v[186:189], v[116:119]
	v_mfma_f32_16x16x32_bf16 v[108:111], v[178:181], v[186:189], v[108:111]
	v_mfma_f32_16x16x32_bf16 v[100:103], v[170:173], v[194:197], v[100:103]
	v_mfma_f32_16x16x32_bf16 v[92:95], v[178:181], v[194:197], v[92:95]
	v_mfma_f32_16x16x32_bf16 v[84:87], v[170:173], v[202:205], v[84:87]
	v_mfma_f32_16x16x32_bf16 v[76:79], v[178:181], v[202:205], v[76:79]
	v_mfma_f32_16x16x32_bf16 v[68:71], v[170:173], v[226:229], v[68:71]
	v_mfma_f32_16x16x32_bf16 v[64:67], v[178:181], v[226:229], v[64:67]
	s_setprio 0
	s_barrier
; #define PG8_STAGE(bufoff, gbase, voff) do { _Pragma("unroll") for (int _i = 0; _i < 2; ++_i) \
;         __builtin_amdgcn_global_load_lds((const unsigned*)((const char*)(gbase) + (voff)[_i]), (PG8_LAS unsigned*)(lds + (bufoff) + ldsw + _i * 8192), 16, 0, 0); } while (0)
; #define PG8_LDA(dst, b, h) do { _Pragma("unroll") for (int m = 0; m < 4; ++m) _Pragma("unroll") for (int k = 0; k < 2; ++k) dst[m][k] = *(const PG8_LAS bf16x8*)(lds + PG8_SA(b, h) + aoff + m * 2048 + k * 1024); } while (0)
; #define PG8_MMA(ai, bj, At, Bt) do { __builtin_amdgcn_s_setprio(1); _Pragma("unroll") for (int m = 0; m < 4; ++m) _Pragma("unroll") for (int n = 0; n < 2; ++n) _Pragma("unroll") for (int k = 0; k < 2; ++k) \
;         acc[ai][bj][m][n] = __builtin_amdgcn_mfma_f32_16x16x32_bf16(Bt[n][k], At[m][k], acc[ai][bj][m][n], 0, 0, 0); __builtin_amdgcn_s_setprio(0); } while (0)
; #define PG8_WAIT_V(n) asm volatile("s_waitcnt vmcnt(" #n ")" ::: "memory")
; #define PG8_WAIT_L(n) asm volatile("s_waitcnt lgkmcnt(" #n ")" ::: "memory")
; #define PG8_BAR __builtin_amdgcn_s_barrier()
; #define PG8_SCHED __builtin_amdgcn_sched_barrier(0)
; template <class Epi, class Sched, bool ALIGN_EPI = false, bool SP2 = false>
; __device__ __forceinline__ void gemm_phase(PG8_LAS unsigned char* lds, const Gemm g, const Sched& S, const Epi& E, const int tid) {
;     ...
;             PG8_LDA(At, 1, 1); PG8_STAGE(PG8_SB(1, 0), b3, voffB); PG8_STAGE(PG8_SB(1, 1), b3 + hstep, voffB); PG8_STAGE(PG8_SA(1, 0), a3, voffA);
;             PG8_WAIT_V(8); PG8_WAIT_L(0); PG8_BAR; PG8_MMA(1, 0, At, B0); PG8_MMA(1, 1, At, B1); PG8_BAR; PG8_SCHED;
;     ...
;         if constexpr (ALIGN_EPI) { if (wr == 0) PG8_BAR; }
	s_add_i32 s13, s13, s19
	v_lshl_add_u64 v[142:143], v[142:143], 0, s[36:37]
	s_mov_b32 m0, s13
	ds_read_b128 v[182:185], v135 offset:49152
	ds_read_b128 v[186:189], v135 offset:50176
	ds_read_b128 v[190:193], v135 offset:51200
	ds_read_b128 v[194:197], v135 offset:52224
	ds_read_b128 v[198:201], v135 offset:53248
	ds_read_b128 v[202:205], v135 offset:54272
	ds_read_b128 v[222:225], v135 offset:55296
	ds_read_b128 v[226:229], v135 offset:56320
	global_load_lds_dwordx4 v[142:143], off
	v_lshl_add_u64 v[142:143], v[150:151], 0, s[36:37]
	s_add_i32 m0, s13, 0x2000
	s_add_i32 s13, s30, s19
	global_load_lds_dwordx4 v[142:143], off
	v_lshl_add_u64 v[142:143], v[206:207], 0, s[36:37]
	s_mov_b32 m0, s13
	s_nop 0
	global_load_lds_dwordx4 v[142:143], off
	v_lshl_add_u64 v[142:143], v[230:231], 0, s[36:37]
	s_add_i32 m0, s13, 0x2000
	s_nop 0
	global_load_lds_dwordx4 v[142:143], off
	v_lshl_add_u64 v[142:143], v[232:233], 0, s[36:37]
	s_mov_b32 m0, s27
	s_nop 0
	global_load_lds_dwordx4 v[142:143], off
	v_lshl_add_u64 v[142:143], v[234:235], 0, s[36:37]
	s_mov_b32 m0, s28
	s_nop 0
	global_load_lds_dwordx4 v[142:143], off
	s_waitcnt vmcnt(8)
	s_waitcnt lgkmcnt(0)
	s_barrier
	s_setprio 1
	s_waitcnt lgkmcnt(0)
	v_mfma_f32_16x16x32_bf16 v[60:63], v[136:139], v[182:185], v[60:63]
	v_mfma_f32_16x16x32_bf16 v[56:59], v[158:161], v[182:185], v[56:59]
	v_mfma_f32_16x16x32_bf16 v[52:55], v[136:139], v[190:193], v[52:55]
	v_mfma_f32_16x16x32_bf16 v[40:43], v[158:161], v[190:193], v[40:43]
	v_mfma_f32_16x16x32_bf16 v[36:39], v[136:139], v[198:201], v[36:39]
	v_mfma_f32_16x16x32_bf16 v[24:27], v[158:161], v[198:201], v[24:27]
	v_mfma_f32_16x16x32_bf16 v[20:23], v[136:139], v[222:225], v[20:23]
	v_mfma_f32_16x16x32_bf16 v[8:11], v[158:161], v[222:225], v[8:11]
	v_mfma_f32_16x16x32_bf16 v[60:63], v[154:157], v[186:189], v[60:63]
	v_mfma_f32_16x16x32_bf16 v[56:59], v[162:165], v[186:189], v[56:59]
	v_mfma_f32_16x16x32_bf16 v[52:55], v[154:157], v[194:197], v[52:55]
	v_mfma_f32_16x16x32_bf16 v[40:43], v[162:165], v[194:197], v[40:43]
	v_mfma_f32_16x16x32_bf16 v[36:39], v[154:157], v[202:205], v[36:39]
	v_mfma_f32_16x16x32_bf16 v[24:27], v[162:165], v[202:205], v[24:27]
	v_mfma_f32_16x16x32_bf16 v[20:23], v[154:157], v[226:229], v[20:23]
	v_mfma_f32_16x16x32_bf16 v[8:11], v[162:165], v[226:229], v[8:11]
	v_mfma_f32_16x16x32_bf16 v[48:51], v[166:169], v[182:185], v[48:51]
	v_mfma_f32_16x16x32_bf16 v[44:47], v[174:177], v[182:185], v[44:47]
	v_mfma_f32_16x16x32_bf16 v[32:35], v[166:169], v[190:193], v[32:35]
	v_mfma_f32_16x16x32_bf16 v[28:31], v[174:177], v[190:193], v[28:31]
	v_mfma_f32_16x16x32_bf16 v[16:19], v[166:169], v[198:201], v[16:19]
	v_mfma_f32_16x16x32_bf16 v[12:15], v[174:177], v[198:201], v[12:15]
	v_mfma_f32_16x16x32_bf16 v[4:7], v[166:169], v[222:225], v[4:7]
	v_mfma_f32_16x16x32_bf16 v[0:3], v[174:177], v[222:225], v[0:3]
	v_mfma_f32_16x16x32_bf16 v[48:51], v[170:173], v[186:189], v[48:51]
	v_mfma_f32_16x16x32_bf16 v[44:47], v[178:181], v[186:189], v[44:47]
	v_mfma_f32_16x16x32_bf16 v[32:35], v[170:173], v[194:197], v[32:35]
	v_mfma_f32_16x16x32_bf16 v[28:31], v[178:181], v[194:197], v[28:31]
	v_mfma_f32_16x16x32_bf16 v[16:19], v[170:173], v[202:205], v[16:19]
	v_mfma_f32_16x16x32_bf16 v[12:15], v[178:181], v[202:205], v[12:15]
	v_mfma_f32_16x16x32_bf16 v[4:7], v[170:173], v[226:229], v[4:7]
	v_mfma_f32_16x16x32_bf16 v[0:3], v[178:181], v[226:229], v[0:3]
	s_setprio 0
	s_barrier
	s_cmp_ge_u32 s12, s26
	s_mov_b32 s14, s12
	s_cbranch_scc0 .LBB0_907
	v_writelane_b32 v253, s40, 6
	s_cmpk_lt_u32 s18, 0x100
	s_nop 0
	v_writelane_b32 v253, s41, 7
	v_writelane_b32 v253, s42, 8
	v_writelane_b32 v253, s43, 9
	v_writelane_b32 v253, s44, 10
	v_writelane_b32 v253, s45, 11
	v_writelane_b32 v253, s46, 12
	v_writelane_b32 v253, s47, 13
	v_writelane_b32 v253, s48, 14
	v_writelane_b32 v253, s49, 15
	v_writelane_b32 v253, s50, 16
	v_writelane_b32 v253, s51, 17
	v_writelane_b32 v253, s52, 18
	v_writelane_b32 v253, s53, 19
	v_writelane_b32 v253, s54, 20
	v_writelane_b32 v253, s55, 21
	s_cbranch_scc0 .LBB0_910
	s_barrier

; #define PG8_STAGE(bufoff, gbase, voff) do { _Pragma("unroll") for (int _i = 0; _i < 2; ++_i) \
;         __builtin_amdgcn_global_load_lds((const unsigned*)((const char*)(gbase) + (voff)[_i]), (PG8_LAS unsigned*)(lds + (bufoff) + ldsw + _i * 8192), 16, 0, 0); } while (0)
; #define PG8_LDA(dst, b, h) do { _Pragma("unroll") for (int m = 0; m < 4; ++m) _Pragma("unroll") for (int k = 0; k < 2; ++k) dst[m][k] = *(const PG8_LAS bf16x8*)(lds + PG8_SA(b, h) + aoff + m * 2048 + k * 1024); } while (0)
; #define PG8_LDB(dst, b, h) do { _Pragma("unroll") for (int n = 0; n < 2; ++n) _Pragma("unroll") for (int k = 0; k < 2; ++k) dst[n][k] = *(const PG8_LAS bf16x8*)(lds + PG8_SB(b, h) + boff + n * 2048 + k * 1024); } while (0)
; #define PG8_MMA(ai, bj, At, Bt) do { __builtin_amdgcn_s_setprio(1); _Pragma("unroll") for (int m = 0; m < 4; ++m) _Pragma("unroll") for (int n = 0; n < 2; ++n) _Pragma("unroll") for (int k = 0; k < 2; ++k) \
;         acc[ai][bj][m][n] = __builtin_amdgcn_mfma_f32_16x16x32_bf16(Bt[n][k], At[m][k], acc[ai][bj][m][n], 0, 0, 0); __builtin_amdgcn_s_setprio(0); } while (0)
; #define PG8_WAIT_V(n) asm volatile("s_waitcnt vmcnt(" #n ")" ::: "memory")
; #define PG8_WAIT_L(n) asm volatile("s_waitcnt lgkmcnt(" #n ")" ::: "memory")
; template <class Epi, class Sched, bool ALIGN_EPI = false, bool SP2 = false>
; __device__ __forceinline__ void gemm_phase(PG8_LAS unsigned char* lds, const Gemm g, const Sched& S, const Epi& E, const int tid) {
;     ...
;             const bool last = (t == nt - 2);
;             const char* a1 = cA + (size_t)(t + 1) * kstep;
;             const char* a2 = last ? nA : cA + (size_t)(t + 2) * kstep; const char* b2 = last ? nB : cB + (size_t)(t + 2) * kstep;
;             const char* a3 = a2 + kstep; const char* b3 = b2 + kstep;
;             if (last && has_next) S.a_ready(nxt);
;             if constexpr (SP2) {
;             PG8_LDB(B0, 0, 0); PG8_LDB(B1, 0, 1); PG8_SCHED; PG8_LDA(At, 0, 0); PG8_STAGE(PG8_SA(1, 1), a1 + hstep, voffA);
;             PG8_WAIT_V(8); PG8_WAIT_L(0); PG8_BAR; PG8_MMA(0, 0, At, B0); PG8_MMA(0, 1, At, B1); PG8_BAR; PG8_SCHED;
;             PG8_LDA(At, 0, 1); PG8_STAGE(PG8_SB(0, 0), b2, voffB); PG8_STAGE(PG8_SB(0, 1), b2 + hstep, voffB); PG8_STAGE(PG8_SA(0, 0), a2, voffA);
;             PG8_WAIT_V(8); PG8_WAIT_L(0); PG8_BAR; PG8_MMA(1, 0, At, B0); PG8_MMA(1, 1, At, B1); PG8_BAR; PG8_SCHED;
.LBB0_921:
	s_add_u32 s18, s16, 0xfffc0080
	s_addc_u32 s19, s17, -1
	s_add_i32 s43, 0, 0x10000
	s_cmp_eq_u32 s42, 12
	s_cselect_b32 s21, s9, s19
	s_cselect_b32 s20, s38, s18
	v_add_u32_e32 v138, s43, v141
	s_cselect_b32 s19, s7, s41
	s_cselect_b32 s18, s39, s40
	s_add_i32 s46, 0, 0x14000
	ds_read_b128 v[154:157], v138
	ds_read_b128 v[158:161], v138 offset:1024
	ds_read_b128 v[162:165], v138 offset:2048
	ds_read_b128 v[166:169], v138 offset:3072
	v_add_u32_e32 v138, s46, v141
	ds_read_b128 v[170:173], v138
	ds_read_b128 v[174:177], v138 offset:1024
	ds_read_b128 v[178:181], v138 offset:2048
	ds_read_b128 v[182:185], v138 offset:3072
	v_lshl_add_u64 v[138:139], s[16:17], 0, v[134:135]
	s_add_i32 m0, s15, 0xc000
	ds_read_b128 v[186:189], v143
	ds_read_b128 v[190:193], v143 offset:1024
	ds_read_b128 v[194:197], v143 offset:2048
	ds_read_b128 v[198:201], v143 offset:3072
	ds_read_b128 v[202:205], v143 offset:4096
	ds_read_b128 v[222:225], v143 offset:5120
	ds_read_b128 v[226:229], v143 offset:6144
	ds_read_b128 v[230:233], v143 offset:7168
	global_load_lds_dwordx4 v[138:139], off
	v_lshl_add_u64 v[138:139], s[16:17], 0, v[136:137]
	s_add_i32 m0, s15, 0xe000
	s_nop 0
	global_load_lds_dwordx4 v[138:139], off
	s_waitcnt vmcnt(8)
	s_waitcnt lgkmcnt(0)
	s_barrier
	s_setprio 1
	s_waitcnt lgkmcnt(0)
	v_mfma_f32_16x16x32_bf16 v[124:127], v[154:157], v[186:189], v[124:127]
	v_mfma_f32_16x16x32_bf16 v[120:123], v[162:165], v[186:189], v[120:123]
	v_mfma_f32_16x16x32_bf16 v[108:111], v[154:157], v[194:197], v[108:111]
	v_mfma_f32_16x16x32_bf16 v[104:107], v[162:165], v[194:197], v[104:107]
	v_mfma_f32_16x16x32_bf16 v[92:95], v[154:157], v[202:205], v[92:95]
	v_mfma_f32_16x16x32_bf16 v[88:91], v[162:165], v[202:205], v[88:91]
	v_mfma_f32_16x16x32_bf16 v[76:79], v[154:157], v[226:229], v[76:79]
	v_mfma_f32_16x16x32_bf16 v[72:75], v[162:165], v[226:229], v[72:75]
	v_mfma_f32_16x16x32_bf16 v[124:127], v[158:161], v[190:193], v[124:127]
	v_mfma_f32_16x16x32_bf16 v[120:123], v[166:169], v[190:193], v[120:123]
	v_mfma_f32_16x16x32_bf16 v[108:111], v[158:161], v[198:201], v[108:111]
	v_mfma_f32_16x16x32_bf16 v[104:107], v[166:169], v[198:201], v[104:107]
	v_mfma_f32_16x16x32_bf16 v[92:95], v[158:161], v[222:225], v[92:95]
	v_mfma_f32_16x16x32_bf16 v[88:91], v[166:169], v[222:225], v[88:91]
	v_mfma_f32_16x16x32_bf16 v[76:79], v[158:161], v[230:233], v[76:79]
	v_mfma_f32_16x16x32_bf16 v[72:75], v[166:169], v[230:233], v[72:75]
	v_mfma_f32_16x16x32_bf16 v[116:119], v[170:173], v[186:189], v[116:119]
	v_mfma_f32_16x16x32_bf16 v[112:115], v[178:181], v[186:189], v[112:115]
	v_mfma_f32_16x16x32_bf16 v[100:103], v[170:173], v[194:197], v[100:103]
	v_mfma_f32_16x16x32_bf16 v[96:99], v[178:181], v[194:197], v[96:99]
	v_mfma_f32_16x16x32_bf16 v[84:87], v[170:173], v[202:205], v[84:87]
	v_mfma_f32_16x16x32_bf16 v[80:83], v[178:181], v[202:205], v[80:83]
	v_mfma_f32_16x16x32_bf16 v[68:71], v[170:173], v[226:229], v[68:71]
	v_mfma_f32_16x16x32_bf16 v[64:67], v[178:181], v[226:229], v[64:67]
	v_mfma_f32_16x16x32_bf16 v[116:119], v[174:177], v[190:193], v[116:119]
	v_mfma_f32_16x16x32_bf16 v[112:115], v[182:185], v[190:193], v[112:115]
	v_mfma_f32_16x16x32_bf16 v[100:103], v[174:177], v[198:201], v[100:103]
	v_mfma_f32_16x16x32_bf16 v[96:99], v[182:185], v[198:201], v[96:99]
	v_mfma_f32_16x16x32_bf16 v[84:87], v[174:177], v[222:225], v[84:87]
	v_mfma_f32_16x16x32_bf16 v[80:83], v[182:185], v[222:225], v[80:83]
	v_mfma_f32_16x16x32_bf16 v[68:71], v[174:177], v[230:233], v[68:71]
	v_mfma_f32_16x16x32_bf16 v[64:67], v[182:185], v[230:233], v[64:67]
	s_setprio 0
	s_barrier
	s_add_i32 s43, s43, s27
	v_lshl_add_u64 v[138:139], s[18:19], 0, v[146:147]
	s_mov_b32 m0, s43
	ds_read_b128 v[186:189], v143 offset:16384
	ds_read_b128 v[190:193], v143 offset:17408
	ds_read_b128 v[194:197], v143 offset:18432
	ds_read_b128 v[198:201], v143 offset:19456
	ds_read_b128 v[202:205], v143 offset:20480
	ds_read_b128 v[222:225], v143 offset:21504
	ds_read_b128 v[226:229], v143 offset:22528
	ds_read_b128 v[230:233], v143 offset:23552
	global_load_lds_dwordx4 v[138:139], off
	s_add_i32 m0, s43, 0x2000
	s_add_u32 s44, s18, 0x40000
	v_lshl_add_u64 v[234:235], s[18:19], 0, v[132:133]
	s_addc_u32 s45, s19, 0
	s_add_i32 s43, s46, s27
	global_load_lds_dwordx4 v[234:235], off
	v_lshl_add_u64 v[236:237], s[44:45], 0, v[146:147]
	s_mov_b32 m0, s43
	v_lshl_add_u64 v[238:239], s[20:21], 0, v[130:131]
	global_load_lds_dwordx4 v[236:237], off
	v_lshl_add_u64 v[236:237], s[44:45], 0, v[132:133]
	s_add_i32 m0, s43, 0x2000
	s_nop 0
	global_load_lds_dwordx4 v[236:237], off
	v_lshl_add_u64 v[236:237], s[20:21], 0, v[128:129]
	s_mov_b32 m0, s15
	s_nop 0
	global_load_lds_dwordx4 v[236:237], off
	s_mov_b32 m0, s29
	s_nop 0
	global_load_lds_dwordx4 v[238:239], off
	s_waitcnt vmcnt(8)
	s_waitcnt lgkmcnt(0)
	s_barrier
; #define PG8_STAGE(bufoff, gbase, voff) do { _Pragma("unroll") for (int _i = 0; _i < 2; ++_i) \
;         __builtin_amdgcn_global_load_lds((const unsigned*)((const char*)(gbase) + (voff)[_i]), (PG8_LAS unsigned*)(lds + (bufoff) + ldsw + _i * 8192), 16, 0, 0); } while (0)
; #define PG8_LDA(dst, b, h) do { _Pragma("unroll") for (int m = 0; m < 4; ++m) _Pragma("unroll") for (int k = 0; k < 2; ++k) dst[m][k] = *(const PG8_LAS bf16x8*)(lds + PG8_SA(b, h) + aoff + m * 2048 + k * 1024); } while (0)
; #define PG8_LDB(dst, b, h) do { _Pragma("unroll") for (int n = 0; n < 2; ++n) _Pragma("unroll") for (int k = 0; k < 2; ++k) dst[n][k] = *(const PG8_LAS bf16x8*)(lds + PG8_SB(b, h) + boff + n * 2048 + k * 1024); } while (0)
; #define PG8_MMA(ai, bj, At, Bt) do { __builtin_amdgcn_s_setprio(1); _Pragma("unroll") for (int m = 0; m < 4; ++m) _Pragma("unroll") for (int n = 0; n < 2; ++n) _Pragma("unroll") for (int k = 0; k < 2; ++k) \
;         acc[ai][bj][m][n] = __builtin_amdgcn_mfma_f32_16x16x32_bf16(Bt[n][k], At[m][k], acc[ai][bj][m][n], 0, 0, 0); __builtin_amdgcn_s_setprio(0); } while (0)
; #define PG8_WAIT_V(n) asm volatile("s_waitcnt vmcnt(" #n ")" ::: "memory")
; #define PG8_WAIT_L(n) asm volatile("s_waitcnt lgkmcnt(" #n ")" ::: "memory")
; #define PG8_BAR __builtin_amdgcn_s_barrier()
; #define PG8_SCHED __builtin_amdgcn_sched_barrier(0)
; template <class Epi, class Sched, bool ALIGN_EPI = false, bool SP2 = false>
; __device__ __forceinline__ void gemm_phase(PG8_LAS unsigned char* lds, const Gemm g, const Sched& S, const Epi& E, const int tid) {
;     ...
;             PG8_WAIT_V(8); PG8_WAIT_L(0); PG8_BAR; PG8_MMA(1, 0, At, B0); PG8_MMA(1, 1, At, B1); PG8_BAR; PG8_SCHED;
;             PG8_LDB(B0, 1, 0); PG8_LDB(B1, 1, 1); PG8_SCHED; PG8_LDA(At, 1, 0); PG8_STAGE(PG8_SA(0, 1), a2 + hstep, voffA);
;             PG8_WAIT_V(8); PG8_WAIT_L(0); PG8_BAR; PG8_MMA(0, 0, At, B0); PG8_MMA(0, 1, At, B1); PG8_BAR; PG8_SCHED;
	s_setprio 1
	s_waitcnt lgkmcnt(0)
	v_mfma_f32_16x16x32_bf16 v[60:63], v[154:157], v[186:189], v[60:63]
	v_mfma_f32_16x16x32_bf16 v[56:59], v[162:165], v[186:189], v[56:59]
	v_mfma_f32_16x16x32_bf16 v[44:47], v[154:157], v[194:197], v[44:47]
	v_mfma_f32_16x16x32_bf16 v[40:43], v[162:165], v[194:197], v[40:43]
	v_mfma_f32_16x16x32_bf16 v[28:31], v[154:157], v[202:205], v[28:31]
	v_mfma_f32_16x16x32_bf16 v[24:27], v[162:165], v[202:205], v[24:27]
	v_mfma_f32_16x16x32_bf16 v[12:15], v[154:157], v[226:229], v[12:15]
	v_mfma_f32_16x16x32_bf16 v[4:7], v[162:165], v[226:229], v[4:7]
	v_mfma_f32_16x16x32_bf16 v[60:63], v[158:161], v[190:193], v[60:63]
	v_mfma_f32_16x16x32_bf16 v[56:59], v[166:169], v[190:193], v[56:59]
	v_mfma_f32_16x16x32_bf16 v[44:47], v[158:161], v[198:201], v[44:47]
	v_mfma_f32_16x16x32_bf16 v[40:43], v[166:169], v[198:201], v[40:43]
	v_mfma_f32_16x16x32_bf16 v[28:31], v[158:161], v[222:225], v[28:31]
	v_mfma_f32_16x16x32_bf16 v[24:27], v[166:169], v[222:225], v[24:27]
	v_mfma_f32_16x16x32_bf16 v[12:15], v[158:161], v[230:233], v[12:15]
	v_mfma_f32_16x16x32_bf16 v[4:7], v[166:169], v[230:233], v[4:7]
	v_mfma_f32_16x16x32_bf16 v[52:55], v[170:173], v[186:189], v[52:55]
	v_mfma_f32_16x16x32_bf16 v[48:51], v[178:181], v[186:189], v[48:51]
	v_mfma_f32_16x16x32_bf16 v[36:39], v[170:173], v[194:197], v[36:39]
	v_mfma_f32_16x16x32_bf16 v[32:35], v[178:181], v[194:197], v[32:35]
	v_mfma_f32_16x16x32_bf16 v[20:23], v[170:173], v[202:205], v[20:23]
	v_mfma_f32_16x16x32_bf16 v[16:19], v[178:181], v[202:205], v[16:19]
	v_mfma_f32_16x16x32_bf16 v[8:11], v[170:173], v[226:229], v[8:11]
	v_mfma_f32_16x16x32_bf16 v[0:3], v[178:181], v[226:229], v[0:3]
	v_mfma_f32_16x16x32_bf16 v[52:55], v[174:177], v[190:193], v[52:55]
	v_mfma_f32_16x16x32_bf16 v[48:51], v[182:185], v[190:193], v[48:51]
	v_mfma_f32_16x16x32_bf16 v[36:39], v[174:177], v[198:201], v[36:39]
	v_mfma_f32_16x16x32_bf16 v[32:35], v[182:185], v[198:201], v[32:35]
	v_mfma_f32_16x16x32_bf16 v[20:23], v[174:177], v[222:225], v[20:23]
	v_mfma_f32_16x16x32_bf16 v[16:19], v[182:185], v[222:225], v[16:19]
	v_mfma_f32_16x16x32_bf16 v[8:11], v[174:177], v[230:233], v[8:11]
	v_mfma_f32_16x16x32_bf16 v[0:3], v[182:185], v[230:233], v[0:3]
	s_setprio 0
	s_barrier
	s_add_i32 s43, 0, 0x18000
	v_add_u32_e32 v150, s43, v141
	s_add_i32 s44, 0, 0x1c000
	ds_read_b128 v[154:157], v150
	ds_read_b128 v[158:161], v150 offset:1024
	ds_read_b128 v[162:165], v150 offset:2048
	ds_read_b128 v[166:169], v150 offset:3072
	v_add_u32_e32 v150, s44, v141
	ds_read_b128 v[170:173], v150
	ds_read_b128 v[174:177], v150 offset:1024
	ds_read_b128 v[178:181], v150 offset:2048
	ds_read_b128 v[182:185], v150 offset:3072
	s_add_u32 s20, s20, 0x40000
	s_addc_u32 s21, s21, 0
	s_mov_b32 m0, s30
	v_lshl_add_u64 v[240:241], s[20:21], 0, v[128:129]
	ds_read_b128 v[186:189], v143 offset:32768
	ds_read_b128 v[190:193], v143 offset:33792
	ds_read_b128 v[194:197], v143 offset:34816
	ds_read_b128 v[198:201], v143 offset:35840
	ds_read_b128 v[202:205], v143 offset:36864
	ds_read_b128 v[222:225], v143 offset:37888
	ds_read_b128 v[226:229], v143 offset:38912
	ds_read_b128 v[230:233], v143 offset:39936
	global_load_lds_dwordx4 v[240:241], off
	v_lshl_add_u64 v[240:241], s[20:21], 0, v[130:131]
	s_mov_b32 m0, s31
	s_nop 0
	global_load_lds_dwordx4 v[240:241], off
	s_waitcnt vmcnt(8)
	s_waitcnt lgkmcnt(0)
	s_barrier
	s_setprio 1
	s_waitcnt lgkmcnt(0)
	v_mfma_f32_16x16x32_bf16 v[124:127], v[154:157], v[186:189], v[124:127]
	v_mfma_f32_16x16x32_bf16 v[120:123], v[162:165], v[186:189], v[120:123]
	v_mfma_f32_16x16x32_bf16 v[108:111], v[154:157], v[194:197], v[108:111]
	v_mfma_f32_16x16x32_bf16 v[104:107], v[162:165], v[194:197], v[104:107]
	v_mfma_f32_16x16x32_bf16 v[92:95], v[154:157], v[202:205], v[92:95]
	v_mfma_f32_16x16x32_bf16 v[88:91], v[162:165], v[202:205], v[88:91]
	v_mfma_f32_16x16x32_bf16 v[76:79], v[154:157], v[226:229], v[76:79]
	v_mfma_f32_16x16x32_bf16 v[72:75], v[162:165], v[226:229], v[72:75]
	v_mfma_f32_16x16x32_bf16 v[124:127], v[158:161], v[190:193], v[124:127]
	v_mfma_f32_16x16x32_bf16 v[120:123], v[166:169], v[190:193], v[120:123]
	v_mfma_f32_16x16x32_bf16 v[108:111], v[158:161], v[198:201], v[108:111]
	v_mfma_f32_16x16x32_bf16 v[104:107], v[166:169], v[198:201], v[104:107]
	v_mfma_f32_16x16x32_bf16 v[92:95], v[158:161], v[222:225], v[92:95]
	v_mfma_f32_16x16x32_bf16 v[88:91], v[166:169], v[222:225], v[88:91]
	v_mfma_f32_16x16x32_bf16 v[76:79], v[158:161], v[230:233], v[76:79]
	v_mfma_f32_16x16x32_bf16 v[72:75], v[166:169], v[230:233], v[72:75]
	v_mfma_f32_16x16x32_bf16 v[116:119], v[170:173], v[186:189], v[116:119]
	v_mfma_f32_16x16x32_bf16 v[112:115], v[178:181], v[186:189], v[112:115]
	v_mfma_f32_16x16x32_bf16 v[100:103], v[170:173], v[194:197], v[100:103]
	v_mfma_f32_16x16x32_bf16 v[96:99], v[178:181], v[194:197], v[96:99]
	v_mfma_f32_16x16x32_bf16 v[84:87], v[170:173], v[202:205], v[84:87]
	v_mfma_f32_16x16x32_bf16 v[80:83], v[178:181], v[202:205], v[80:83]
	v_mfma_f32_16x16x32_bf16 v[68:71], v[170:173], v[226:229], v[68:71]
	v_mfma_f32_16x16x32_bf16 v[64:67], v[178:181], v[226:229], v[64:67]
	v_mfma_f32_16x16x32_bf16 v[116:119], v[174:177], v[190:193], v[116:119]
	v_mfma_f32_16x16x32_bf16 v[112:115], v[182:185], v[190:193], v[112:115]
	v_mfma_f32_16x16x32_bf16 v[100:103], v[174:177], v[198:201], v[100:103]
	v_mfma_f32_16x16x32_bf16 v[96:99], v[182:185], v[198:201], v[96:99]
	v_mfma_f32_16x16x32_bf16 v[84:87], v[174:177], v[222:225], v[84:87]
	v_mfma_f32_16x16x32_bf16 v[80:83], v[182:185], v[222:225], v[80:83]
	v_mfma_f32_16x16x32_bf16 v[68:71], v[174:177], v[230:233], v[68:71]
	v_mfma_f32_16x16x32_bf16 v[64:67], v[182:185], v[230:233], v[64:67]
	s_setprio 0
	s_barrier
; #define PG8_STAGE(bufoff, gbase, voff) do { _Pragma("unroll") for (int _i = 0; _i < 2; ++_i) \
;         __builtin_amdgcn_global_load_lds((const unsigned*)((const char*)(gbase) + (voff)[_i]), (PG8_LAS unsigned*)(lds + (bufoff) + ldsw + _i * 8192), 16, 0, 0); } while (0)
; #define PG8_LDA(dst, b, h) do { _Pragma("unroll") for (int m = 0; m < 4; ++m) _Pragma("unroll") for (int k = 0; k < 2; ++k) dst[m][k] = *(const PG8_LAS bf16x8*)(lds + PG8_SA(b, h) + aoff + m * 2048 + k * 1024); } while (0)
; #define PG8_MMA(ai, bj, At, Bt) do { __builtin_amdgcn_s_setprio(1); _Pragma("unroll") for (int m = 0; m < 4; ++m) _Pragma("unroll") for (int n = 0; n < 2; ++n) _Pragma("unroll") for (int k = 0; k < 2; ++k) \
;         acc[ai][bj][m][n] = __builtin_amdgcn_mfma_f32_16x16x32_bf16(Bt[n][k], At[m][k], acc[ai][bj][m][n], 0, 0, 0); __builtin_amdgcn_s_setprio(0); } while (0)
; #define PG8_WAIT_V(n) asm volatile("s_waitcnt vmcnt(" #n ")" ::: "memory")
; #define PG8_WAIT_L(n) asm volatile("s_waitcnt lgkmcnt(" #n ")" ::: "memory")
; #define PG8_BAR __builtin_amdgcn_s_barrier()
; #define PG8_SCHED __builtin_amdgcn_sched_barrier(0)
; template <class Epi, class Sched, bool ALIGN_EPI = false, bool SP2 = false>
; __device__ __forceinline__ void gemm_phase(PG8_LAS unsigned char* lds, const Gemm g, const Sched& S, const Epi& E, const int tid) {
;     ...
;         for (int t = 0; t < nt; t += 2) {
;             const bool last = (t == nt - 2);
;     ...
;             PG8_LDA(At, 1, 1); PG8_STAGE(PG8_SB(1, 0), b3, voffB); PG8_STAGE(PG8_SB(1, 1), b3 + hstep, voffB); PG8_STAGE(PG8_SA(1, 0), a3, voffA);
;             PG8_WAIT_V(8); PG8_WAIT_L(0); PG8_BAR; PG8_MMA(1, 0, At, B0); PG8_MMA(1, 1, At, B1); PG8_BAR; PG8_SCHED;
	s_add_i32 s20, s43, s27
	v_lshl_add_u64 v[138:139], v[138:139], 0, s[48:49]
	s_mov_b32 m0, s20
	ds_read_b128 v[186:189], v143 offset:49152
	ds_read_b128 v[190:193], v143 offset:50176
	ds_read_b128 v[194:197], v143 offset:51200
	ds_read_b128 v[198:201], v143 offset:52224
	ds_read_b128 v[202:205], v143 offset:53248
	ds_read_b128 v[222:225], v143 offset:54272
	ds_read_b128 v[226:229], v143 offset:55296
	ds_read_b128 v[230:233], v143 offset:56320
	global_load_lds_dwordx4 v[138:139], off
	s_add_i32 m0, s20, 0x2000
	s_add_u32 s18, s18, 0x40080
	v_lshl_add_u64 v[138:139], v[234:235], 0, s[48:49]
	s_addc_u32 s19, s19, 0
	s_add_i32 s20, s44, s27
	global_load_lds_dwordx4 v[138:139], off
	v_lshl_add_u64 v[138:139], s[18:19], 0, v[146:147]
	s_mov_b32 m0, s20
	s_nop 0
	global_load_lds_dwordx4 v[138:139], off
	v_lshl_add_u64 v[138:139], s[18:19], 0, v[132:133]
	s_add_i32 m0, s20, 0x2000
	s_nop 0
	global_load_lds_dwordx4 v[138:139], off
	v_lshl_add_u64 v[138:139], v[236:237], 0, s[48:49]
	s_mov_b32 m0, s34
	s_nop 0
	global_load_lds_dwordx4 v[138:139], off
	v_lshl_add_u64 v[138:139], v[238:239], 0, s[48:49]
	s_mov_b32 m0, s35
	s_nop 0
	global_load_lds_dwordx4 v[138:139], off
	s_waitcnt vmcnt(8)
	s_waitcnt lgkmcnt(0)
	s_barrier
	s_setprio 1
	s_waitcnt lgkmcnt(0)
	v_mfma_f32_16x16x32_bf16 v[60:63], v[154:157], v[186:189], v[60:63]
	v_mfma_f32_16x16x32_bf16 v[56:59], v[162:165], v[186:189], v[56:59]
	v_mfma_f32_16x16x32_bf16 v[44:47], v[154:157], v[194:197], v[44:47]
	v_mfma_f32_16x16x32_bf16 v[40:43], v[162:165], v[194:197], v[40:43]
	v_mfma_f32_16x16x32_bf16 v[28:31], v[154:157], v[202:205], v[28:31]
	v_mfma_f32_16x16x32_bf16 v[24:27], v[162:165], v[202:205], v[24:27]
	v_mfma_f32_16x16x32_bf16 v[12:15], v[154:157], v[226:229], v[12:15]
	v_mfma_f32_16x16x32_bf16 v[4:7], v[162:165], v[226:229], v[4:7]
	v_mfma_f32_16x16x32_bf16 v[60:63], v[158:161], v[190:193], v[60:63]
	v_mfma_f32_16x16x32_bf16 v[56:59], v[166:169], v[190:193], v[56:59]
	v_mfma_f32_16x16x32_bf16 v[44:47], v[158:161], v[198:201], v[44:47]
	v_mfma_f32_16x16x32_bf16 v[40:43], v[166:169], v[198:201], v[40:43]
	v_mfma_f32_16x16x32_bf16 v[28:31], v[158:161], v[222:225], v[28:31]
	v_mfma_f32_16x16x32_bf16 v[24:27], v[166:169], v[222:225], v[24:27]
	v_mfma_f32_16x16x32_bf16 v[12:15], v[158:161], v[230:233], v[12:15]
	v_mfma_f32_16x16x32_bf16 v[4:7], v[166:169], v[230:233], v[4:7]
	v_mfma_f32_16x16x32_bf16 v[52:55], v[170:173], v[186:189], v[52:55]
	v_mfma_f32_16x16x32_bf16 v[48:51], v[178:181], v[186:189], v[48:51]
	v_mfma_f32_16x16x32_bf16 v[36:39], v[170:173], v[194:197], v[36:39]
	v_mfma_f32_16x16x32_bf16 v[32:35], v[178:181], v[194:197], v[32:35]
	v_mfma_f32_16x16x32_bf16 v[20:23], v[170:173], v[202:205], v[20:23]
	v_mfma_f32_16x16x32_bf16 v[16:19], v[178:181], v[202:205], v[16:19]
	v_mfma_f32_16x16x32_bf16 v[8:11], v[170:173], v[226:229], v[8:11]
	v_mfma_f32_16x16x32_bf16 v[0:3], v[178:181], v[226:229], v[0:3]
	v_mfma_f32_16x16x32_bf16 v[52:55], v[174:177], v[190:193], v[52:55]
	v_mfma_f32_16x16x32_bf16 v[48:51], v[182:185], v[190:193], v[48:51]
	v_mfma_f32_16x16x32_bf16 v[36:39], v[174:177], v[198:201], v[36:39]
	v_mfma_f32_16x16x32_bf16 v[32:35], v[182:185], v[198:201], v[32:35]
	v_mfma_f32_16x16x32_bf16 v[20:23], v[174:177], v[222:225], v[20:23]
	v_mfma_f32_16x16x32_bf16 v[16:19], v[182:185], v[222:225], v[16:19]
	v_mfma_f32_16x16x32_bf16 v[8:11], v[174:177], v[230:233], v[8:11]
	v_mfma_f32_16x16x32_bf16 v[0:3], v[182:185], v[230:233], v[0:3]
	s_setprio 0
	s_barrier
	s_add_i32 s42, s42, 2
	s_add_u32 s16, s16, 0x100
	s_addc_u32 s17, s17, 0
	s_add_u32 s40, s40, 0x100
	s_addc_u32 s41, s41, 0
	s_cmp_gt_u32 s42, 13
	s_cbranch_scc0 .LBB0_921
	s_and_b64 vcc, exec, s[4:5]
	s_cbranch_vccz .LBB0_924
	s_barrier
